# P13/P15 fused-norm epilogues: all residual-row loads issued upfront into free VGPRs (ladder de-serialised); P6 decode-rows LRU tile: state_h loads of channel tiles 1-4 batched
# speedup vs baseline: 1.0138x; 1.0080x over previous
; #define LAS __attribute__((address_space(3)))
; template <int PASS, bool SAMP> __device__ __forceinline__ void lru_tile(const Args& a, int z, unsigned char* ws, LAS unsigned char* lds, int n, int row0, int tib0, int lane, int wave, ...
;     ...
;     for (int ct = 0; ct < 5; ++ct) {
;         f32x4 ar = {0.f, 0.f, 0.f, 0.f}, ai = {0.f, 0.f, 0.f, 0.f};
; #pragma unroll
;         for (int j = 0; j < 3; ++j) {
;             const bf16x8 br = *(const LAS bf16x8*)(lds + L2_LW + (ct * 16 + l15) * 208 + (32 * j + 8 * g4) * 2);
;             const bf16x8 bi = *(const LAS bf16x8*)(lds + L2_LW + (80 + ct * 16 + l15) * 208 + (32 * j + 8 * g4) * 2);
;             ar = __builtin_amdgcn_mfma_f32_16x16x32_bf16(af[j], br, ar, 0, 0, 0);
;             ai = __builtin_amdgcn_mfma_f32_16x16x32_bf16(af[j], bi, ai, 0, 0, 0);
;         }
;         const int ch = ct * 16 + l15;
;         float av[4], bv[4];
; #pragma unroll
;         for (int i = 0; i < 4; ++i) {
;             const float r = __builtin_amdgcn_rcpf(1.f + __builtin_amdgcn_exp2f(ar[i] + gba[ct])), gi = __builtin_amdgcn_rcpf(1.f + __builtin_amdgcn_exp2f(ai[i] + gbi[ct]));
;             av[i] = __builtin_amdgcn_exp2f(r * gsp[ct]);
;             bv[i] = __builtin_amdgcn_sqrtf(__builtin_fmaf(-av[i], av[i], 1.f)) * gi * xt[(4 * g4 + i) * L2_TPITCH + ch];
;         }
;         float hv[4];
;         if constexpr (SAMP) {
;             const float* sh = (const float*)a.in[I_SH + z];
; #pragma unroll
;             for (int i = 0; i < 4; ++i) { const int s = row0 - MP + 4 * g4 + i; hv[i] = av[i] * sh[(size_t)s * DRNN + ch0 + ch] + bv[i]; ((float*)a.in[I_OUT + z])[O_H_S + (size_t)s * DRNN + ch0 + ch] = hv[i]; }
.LBB0_1147:
	s_or_b64 exec, exec, s[16:17]
	s_waitcnt lgkmcnt(0)
	s_load_dwordx2 s[16:17], s[40:41], 0x30
	s_lshl_b32 s26, s81, 2
	v_mov_b32_e32 v161, v0
	v_lshl_add_u32 v44, v173, 2, s59
	v_cvt_pk_bf16_f32 v2, v2, v3
	s_waitcnt lgkmcnt(0)
	s_add_u32 s16, s16, s26
	s_addc_u32 s17, s17, 0
	v_lshl_add_u64 v[40:41], s[16:17], 0, v[160:161]
	v_mad_i64_i32 v[26:27], s[16:17], v44, s73, v[40:41]
	global_load_dword v45, v[26:27], off
	v_cvt_pk_bf16_f32 v3, v4, v5
	v_cvt_pk_bf16_f32 v4, v22, v23
	v_cvt_pk_bf16_f32 v5, v24, v25
	v_cvt_pk_bf16_f32 v10, v10, v11
	v_cvt_pk_bf16_f32 v11, v12, v13
	v_cvt_pk_bf16_f32 v12, v6, v7
	v_cvt_pk_bf16_f32 v13, v8, v9
	ds_read_b128 v[22:25], v191
	v_cvt_pk_bf16_f32 v6, v18, v19
	v_cvt_pk_bf16_f32 v7, v20, v21
	ds_read_b128 v[18:21], v191 offset:16640
	ds_read_b128 v[28:31], v191 offset:64
	v_cvt_pk_bf16_f32 v8, v14, v15
	v_cvt_pk_bf16_f32 v9, v16, v17
	s_waitcnt lgkmcnt(2)
	v_mfma_f32_16x16x32_bf16 v[22:25], v[10:13], v[22:25], 0
	ds_read_b128 v[14:17], v191 offset:128
	ds_read_b128 v[32:35], v191 offset:16704
	ds_read_b128 v[36:39], v191 offset:16768
	v_mov_b64_e32 v[42:43], s[14:15]
	s_waitcnt lgkmcnt(3)
	v_mfma_f32_16x16x32_bf16 v[22:25], v[6:9], v[28:31], v[22:25]
	v_mad_i64_i32 v[28:29], s[14:15], v44, s73, v[42:43]
	ds_read2_b32 v[48:49], v139 offset0:128 offset1:144
	s_waitcnt lgkmcnt(3)
	v_mfma_f32_16x16x32_bf16 v[22:25], v[2:5], v[14:17], v[22:25]
	v_or_b32_e32 v46, 1, v44
	ds_read2_b32 v[54:55], v138 offset0:40 offset1:56
	s_mov_b32 s1, s27
	v_mfma_f32_16x16x32_bf16 v[18:21], v[10:13], v[18:21], 0
	s_nop 3
	v_add_f32_e32 v14, v182, v22
	v_exp_f32_e32 v22, v14
	s_waitcnt lgkmcnt(3)
	v_mfma_f32_16x16x32_bf16 v[14:17], v[6:9], v[32:35], v[18:21]
	s_nop 2
	v_lshl_add_u64 v[18:19], v[28:29], 0, s[26:27]
	v_add_f32_e32 v20, 1.0, v22
	s_waitcnt lgkmcnt(2)
	v_mfma_f32_16x16x32_bf16 v[28:31], v[2:5], v[36:39], v[14:17]
	v_rcp_f32_e32 v20, v20
	v_lshl_add_u64 v[50:51], v[18:19], 0, v[160:161]
	s_nop 0
	v_add_co_u32_e32 v16, vcc, s79, v50
	v_mul_f32_e32 v15, v188, v20
	s_nop 2
	v_add_f32_e32 v14, v181, v28
	v_exp_f32_e32 v14, v14
	v_exp_f32_e32 v20, v15
	v_addc_co_u32_e32 v17, vcc, 0, v51, vcc
	v_add_f32_e32 v14, 1.0, v14
	v_rcp_f32_e32 v18, v14
	v_fma_f32 v14, -v20, v20, 1.0
	v_sqrt_f32_e32 v19, v14
	v_mad_i64_i32 v[14:15], s[14:15], v46, s73, v[40:41]
	v_add_f32_e32 v21, v181, v29
	v_mul_f32_e32 v18, v18, v19
	s_waitcnt lgkmcnt(1)
	v_mul_f32_e32 v28, v48, v18
	v_add_f32_e32 v18, v182, v23
	v_exp_f32_e32 v21, v21
	v_or_b32_e32 v23, 2, v44
	s_waitcnt vmcnt(0)
	v_fmac_f32_e32 v28, v45, v20
	global_store_dword v[16:17], v28, off
	global_load_dword v22, v[14:15], off
	v_exp_f32_e32 v20, v18
	v_mad_i64_i32 v[18:19], s[14:15], v46, s73, v[42:43]
	v_lshl_add_u64 v[18:19], v[18:19], 0, s[26:27]
	v_add_f32_e32 v20, 1.0, v20
	v_rcp_f32_e32 v20, v20
	v_lshl_add_u64 v[52:53], v[18:19], 0, v[160:161]
	v_add_f32_e32 v18, 1.0, v21
	v_rcp_f32_e32 v32, v18
	v_mul_f32_e32 v20, v188, v20
	v_exp_f32_e32 v29, v20
	ds_read2_b32 v[16:17], v139 offset0:192 offset1:212
	v_add_co_u32_e32 v20, vcc, s79, v52
	v_fma_f32 v18, -v29, v29, 1.0
	v_sqrt_f32_e32 v33, v18
	v_addc_co_u32_e32 v21, vcc, 0, v53, vcc
	v_mad_i64_i32 v[18:19], s[14:15], v23, s73, v[40:41]
	v_mul_f32_e32 v32, v32, v33
	s_waitcnt lgkmcnt(0)
	v_mul_f32_e32 v17, v17, v32
	s_waitcnt vmcnt(0)
	v_fmac_f32_e32 v17, v29, v22
	global_store_dword v[20:21], v17, off
	global_load_dword v29, v[18:19], off
	v_add_f32_e32 v20, v182, v24
	v_exp_f32_e32 v22, v20
	v_mad_i64_i32 v[20:21], s[14:15], v23, s73, v[42:43]
	v_add_f32_e32 v23, v181, v30
	v_add_f32_e32 v22, 1.0, v22
	v_rcp_f32_e32 v22, v22
	v_exp_f32_e32 v23, v23
	v_lshl_add_u64 v[20:21], v[20:21], 0, s[26:27]
	v_lshl_add_u64 v[56:57], v[20:21], 0, v[160:161]
	v_mul_f32_e32 v22, v188, v22
	v_exp_f32_e32 v30, v22
	v_add_f32_e32 v20, 1.0, v23
	v_rcp_f32_e32 v32, v20
	v_add_co_u32_e32 v22, vcc, s79, v56
	v_fma_f32 v20, -v30, v30, 1.0
	v_sqrt_f32_e32 v33, v20
	v_or_b32_e32 v24, 3, v44
	v_addc_co_u32_e32 v23, vcc, 0, v57, vcc
	v_mul_f32_e32 v32, v32, v33
	v_mad_i64_i32 v[20:21], s[14:15], v24, s73, v[40:41]
	s_waitcnt vmcnt(0)
	v_mul_f32_e32 v29, v30, v29
	v_fmac_f32_e32 v29, v54, v32
	global_store_dword v[22:23], v29, off
	global_load_dword v30, v[20:21], off
	global_load_dword v220, v[26:27], off offset:64
	global_load_dword v221, v[14:15], off offset:64
	global_load_dword v222, v[18:19], off offset:64
	global_load_dword v223, v[20:21], off offset:64
	global_load_dword v224, v[26:27], off offset:128
	global_load_dword v225, v[14:15], off offset:128
	global_load_dword v226, v[18:19], off offset:128
	global_load_dword v227, v[20:21], off offset:128
	global_load_dword v228, v[26:27], off offset:192
	global_load_dword v229, v[14:15], off offset:192
	global_load_dword v230, v[18:19], off offset:192
	global_load_dword v231, v[20:21], off offset:192
	global_load_dword v232, v[26:27], off offset:256
	global_load_dword v233, v[14:15], off offset:256
	global_load_dword v234, v[18:19], off offset:256
	global_load_dword v235, v[20:21], off offset:256
	v_add_f32_e32 v22, v182, v25
	v_exp_f32_e32 v22, v22
	v_add_f32_e32 v23, v181, v31
	v_exp_f32_e32 v23, v23
	v_add_f32_e32 v22, 1.0, v22
	v_rcp_f32_e32 v22, v22
	s_nop 0
	v_mul_f32_e32 v22, v188, v22
	v_exp_f32_e32 v25, v22
	v_add_f32_e32 v22, 1.0, v23
	v_rcp_f32_e32 v31, v22
	v_fma_f32 v22, -v25, v25, 1.0
	v_sqrt_f32_e32 v32, v22
	ds_read2_b32 v[22:23], v138 offset0:104 offset1:124
	ds_write_b32 v189, v28 offset:40704
	ds_write_b32 v189, v17 offset:41040
	ds_write_b32 v189, v29 offset:41376
	v_mul_f32_e32 v31, v31, v32
	s_waitcnt vmcnt(0)
; #define LAS __attribute__((address_space(3)))
; template <int PASS, bool SAMP> __device__ __forceinline__ void lru_tile(const Args& a, int z, unsigned char* ws, LAS unsigned char* lds, int n, int row0, int tib0, int lane, int wave, ...
;     ...
;     for (int ct = 0; ct < 5; ++ct) {
;         f32x4 ar = {0.f, 0.f, 0.f, 0.f}, ai = {0.f, 0.f, 0.f, 0.f};
; #pragma unroll
;         for (int j = 0; j < 3; ++j) {
;             const bf16x8 br = *(const LAS bf16x8*)(lds + L2_LW + (ct * 16 + l15) * 208 + (32 * j + 8 * g4) * 2);
;             const bf16x8 bi = *(const LAS bf16x8*)(lds + L2_LW + (80 + ct * 16 + l15) * 208 + (32 * j + 8 * g4) * 2);
;             ar = __builtin_amdgcn_mfma_f32_16x16x32_bf16(af[j], br, ar, 0, 0, 0);
;             ai = __builtin_amdgcn_mfma_f32_16x16x32_bf16(af[j], bi, ai, 0, 0, 0);
;         }
;         const int ch = ct * 16 + l15;
;         float av[4], bv[4];
; #pragma unroll
;         for (int i = 0; i < 4; ++i) {
;             const float r = __builtin_amdgcn_rcpf(1.f + __builtin_amdgcn_exp2f(ar[i] + gba[ct])), gi = __builtin_amdgcn_rcpf(1.f + __builtin_amdgcn_exp2f(ai[i] + gbi[ct]));
;             av[i] = __builtin_amdgcn_exp2f(r * gsp[ct]);
;             bv[i] = __builtin_amdgcn_sqrtf(__builtin_fmaf(-av[i], av[i], 1.f)) * gi * xt[(4 * g4 + i) * L2_TPITCH + ch];
;         }
;         float hv[4];
;         if constexpr (SAMP) {
;             const float* sh = (const float*)a.in[I_SH + z];
; #pragma unroll
;             for (int i = 0; i < 4; ++i) { const int s = row0 - MP + 4 * g4 + i; hv[i] = av[i] * sh[(size_t)s * DRNN + ch0 + ch] + bv[i]; ((float*)a.in[I_OUT + z])[O_H_S + (size_t)s * DRNN + ch0 + ch] = hv[i]; }
	v_mul_f32_e32 v17, v25, v30
	v_mad_i64_i32 v[24:25], s[14:15], v24, s73, v[42:43]
	v_lshl_add_u64 v[24:25], v[24:25], 0, s[26:27]
	v_lshl_add_u64 v[58:59], v[24:25], 0, v[160:161]
	s_waitcnt lgkmcnt(3)
	v_fmac_f32_e32 v17, v23, v31
	v_add_co_u32_e32 v24, vcc, s79, v58
	ds_write_b32 v189, v17 offset:41712
	s_nop 0
	v_addc_co_u32_e32 v25, vcc, 0, v59, vcc
	ds_read_b128 v[28:31], v191 offset:3328
	ds_read_b128 v[32:35], v191 offset:19968
	ds_read_b128 v[36:39], v191 offset:3392
	global_store_dword v[24:25], v17, off
	v_mov_b32_e32 v17, v220
	s_waitcnt lgkmcnt(2)
	v_mfma_f32_16x16x32_bf16 v[28:31], v[10:13], v[28:31], 0
	ds_read_b128 v[40:43], v191 offset:3456
	ds_read_b128 v[44:47], v191 offset:20032
	ds_read2_b32 v[60:61], v139 offset0:228 offset1:244
	s_waitcnt lgkmcnt(3)
	v_mfma_f32_16x16x32_bf16 v[28:31], v[6:9], v[36:39], v[28:31]
	ds_read_b128 v[36:39], v191 offset:20096
	s_waitcnt lgkmcnt(3)
	v_mfma_f32_16x16x32_bf16 v[40:43], v[2:5], v[40:43], v[28:31]
	v_mfma_f32_16x16x32_bf16 v[32:35], v[10:13], v[32:35], 0
	s_waitcnt lgkmcnt(2)
	v_mfma_f32_16x16x32_bf16 v[32:35], v[6:9], v[44:47], v[32:35]
	s_nop 4
	v_add_f32_e32 v23, v180, v40
	v_exp_f32_e32 v23, v23
	s_waitcnt lgkmcnt(0)
	v_mfma_f32_16x16x32_bf16 v[30:33], v[2:5], v[36:39], v[32:35]
	v_add_f32_e32 v23, 1.0, v23
	v_rcp_f32_e32 v23, v23
	s_nop 0
	v_mul_f32_e32 v23, v187, v23
	s_nop 3
	v_add_f32_e32 v24, v179, v30
	v_exp_f32_e32 v24, v24
	v_exp_f32_e32 v23, v23
	v_add_f32_e32 v33, v179, v33
	v_exp_f32_e32 v33, v33
	v_add_f32_e32 v24, 1.0, v24
	v_rcp_f32_e32 v28, v24
	v_fma_f32 v24, -v23, v23, 1.0
	v_sqrt_f32_e32 v29, v24
	v_lshl_add_u64 v[24:25], v[50:51], 0, s[38:39]
	v_add_f32_e32 v33, 1.0, v33
	v_rcp_f32_e32 v33, v33
	v_mul_f32_e32 v28, v28, v29
	v_mul_f32_e32 v34, v49, v28
	v_add_f32_e32 v28, v179, v31
	v_exp_f32_e32 v28, v28
	v_fmac_f32_e32 v34, v17, v23
	global_store_dword v[24:25], v34, off offset:64
	v_mov_b32_e32 v17, v221
	v_add_f32_e32 v23, v180, v41
	v_exp_f32_e32 v23, v23
	v_add_f32_e32 v28, 1.0, v28
	v_rcp_f32_e32 v30, v28
	v_add_f32_e32 v23, 1.0, v23
	v_rcp_f32_e32 v23, v23
	s_nop 0
	v_mul_f32_e32 v23, v187, v23
	v_exp_f32_e32 v23, v23
	s_nop 0
	v_fma_f32 v28, -v23, v23, 1.0
	v_sqrt_f32_e32 v31, v28
	v_lshl_add_u64 v[28:29], v[52:53], 0, s[38:39]
	v_mul_f32_e32 v30, v30, v31
	v_mul_f32_e32 v35, v60, v30
	v_add_f32_e32 v30, v179, v32
	v_exp_f32_e32 v30, v30
	v_fmac_f32_e32 v35, v23, v17
	global_store_dword v[28:29], v35, off offset:64
	v_mov_b32_e32 v17, v222
	v_add_f32_e32 v23, v180, v42
	v_exp_f32_e32 v23, v23
	v_add_f32_e32 v30, 1.0, v30
	v_rcp_f32_e32 v32, v30
	v_add_f32_e32 v23, 1.0, v23
	v_rcp_f32_e32 v23, v23
	s_nop 0
	v_mul_f32_e32 v23, v187, v23
	v_exp_f32_e32 v23, v23
	s_nop 0
	v_fma_f32 v30, -v23, v23, 1.0
	v_sqrt_f32_e32 v36, v30
	v_lshl_add_u64 v[30:31], v[56:57], 0, s[38:39]
	ds_read2_b32 v[56:57], v138 offset0:140 offset1:156
	v_mul_f32_e32 v32, v32, v36
	v_mul_f32_e32 v17, v23, v17
	v_fmac_f32_e32 v17, v55, v32
	global_store_dword v[30:31], v17, off offset:64
	v_mov_b32_e32 v23, v223
	v_add_f32_e32 v32, v180, v43
	v_exp_f32_e32 v32, v32
	ds_write_b32 v189, v34 offset:40768
	ds_write_b32 v189, v35 offset:41104
	ds_write_b32 v189, v17 offset:41440
	v_add_f32_e32 v32, 1.0, v32
	v_rcp_f32_e32 v32, v32
	s_nop 0
	v_mul_f32_e32 v32, v187, v32
	v_exp_f32_e32 v32, v32
	s_nop 0
	v_fma_f32 v36, -v32, v32, 1.0
	v_sqrt_f32_e32 v36, v36
	v_mul_f32_e32 v17, v32, v23
	v_mul_f32_e32 v33, v33, v36
	s_waitcnt lgkmcnt(3)
	v_fmac_f32_e32 v17, v56, v33
	ds_write_b32 v189, v17 offset:41776
	ds_read_b128 v[32:35], v191 offset:6656
	ds_read_b128 v[36:39], v191 offset:6720
	s_waitcnt lgkmcnt(1)
	v_mfma_f32_16x16x32_bf16 v[32:35], v[10:13], v[32:35], 0
	ds_read_b128 v[40:43], v191 offset:23296
	ds_read_b128 v[44:47], v191 offset:6784
	ds_read_b128 v[48:51], v191 offset:23360
	ds_read_b128 v[52:55], v191 offset:23424
	s_waitcnt lgkmcnt(4)
	v_mfma_f32_16x16x32_bf16 v[34:37], v[6:9], v[36:39], v[32:35]
	s_nop 2
	v_lshl_add_u64 v[32:33], v[58:59], 0, s[38:39]
	global_store_dword v[32:33], v17, off offset:64
	v_mov_b32_e32 v17, v224
	s_waitcnt lgkmcnt(2)
	v_mfma_f32_16x16x32_bf16 v[34:37], v[2:5], v[44:47], v[34:37]
	ds_read2_b32 v[58:59], v138 offset0:72 offset1:88
	v_mfma_f32_16x16x32_bf16 v[40:43], v[10:13], v[40:43], 0
	s_waitcnt lgkmcnt(2)
	v_mfma_f32_16x16x32_bf16 v[38:41], v[6:9], v[48:51], v[40:43]
	s_nop 3
	v_add_f32_e32 v23, v178, v34
	v_exp_f32_e32 v23, v23
	s_waitcnt lgkmcnt(1)
	v_mfma_f32_16x16x32_bf16 v[38:41], v[2:5], v[52:55], v[38:41]
	ds_read2_b32 v[54:55], v139 offset0:160 offset1:176
	v_add_f32_e32 v23, 1.0, v23
	v_rcp_f32_e32 v23, v23
	s_nop 0
	v_mul_f32_e32 v23, v186, v23
	s_nop 2
	v_add_f32_e32 v34, v177, v38
	v_exp_f32_e32 v34, v34
	v_exp_f32_e32 v23, v23
	v_add_f32_e32 v34, 1.0, v34
	v_fma_f32 v38, -v23, v23, 1.0
	v_rcp_f32_e32 v34, v34
	v_sqrt_f32_e32 v38, v38
	s_nop 0
	v_mul_f32_e32 v34, v34, v38
	s_waitcnt lgkmcnt(0)
; #define LAS __attribute__((address_space(3)))
; template <int PASS, bool SAMP> __device__ __forceinline__ void lru_tile(const Args& a, int z, unsigned char* ws, LAS unsigned char* lds, int n, int row0, int tib0, int lane, int wave, ...
;     ...
;     for (int ct = 0; ct < 5; ++ct) {
;         f32x4 ar = {0.f, 0.f, 0.f, 0.f}, ai = {0.f, 0.f, 0.f, 0.f};
; #pragma unroll
;         for (int j = 0; j < 3; ++j) {
;             const bf16x8 br = *(const LAS bf16x8*)(lds + L2_LW + (ct * 16 + l15) * 208 + (32 * j + 8 * g4) * 2);
;             const bf16x8 bi = *(const LAS bf16x8*)(lds + L2_LW + (80 + ct * 16 + l15) * 208 + (32 * j + 8 * g4) * 2);
;             ar = __builtin_amdgcn_mfma_f32_16x16x32_bf16(af[j], br, ar, 0, 0, 0);
;             ai = __builtin_amdgcn_mfma_f32_16x16x32_bf16(af[j], bi, ai, 0, 0, 0);
;         }
;         const int ch = ct * 16 + l15;
;         float av[4], bv[4];
; #pragma unroll
;         for (int i = 0; i < 4; ++i) {
;             const float r = __builtin_amdgcn_rcpf(1.f + __builtin_amdgcn_exp2f(ar[i] + gba[ct])), gi = __builtin_amdgcn_rcpf(1.f + __builtin_amdgcn_exp2f(ai[i] + gbi[ct]));
;             av[i] = __builtin_amdgcn_exp2f(r * gsp[ct]);
;             bv[i] = __builtin_amdgcn_sqrtf(__builtin_fmaf(-av[i], av[i], 1.f)) * gi * xt[(4 * g4 + i) * L2_TPITCH + ch];
;         }
;         float hv[4];
;         if constexpr (SAMP) {
;             const float* sh = (const float*)a.in[I_SH + z];
; #pragma unroll
;             for (int i = 0; i < 4; ++i) { const int s = row0 - MP + 4 * g4 + i; hv[i] = av[i] * sh[(size_t)s * DRNN + ch0 + ch] + bv[i]; ((float*)a.in[I_OUT + z])[O_H_S + (size_t)s * DRNN + ch0 + ch] = hv[i]; }
	v_mul_f32_e32 v34, v54, v34
	v_fmac_f32_e32 v34, v17, v23
	global_store_dword v[24:25], v34, off offset:128
	v_mov_b32_e32 v17, v225
	v_add_f32_e32 v23, v178, v35
	v_exp_f32_e32 v23, v23
	v_add_f32_e32 v35, v177, v39
	v_exp_f32_e32 v35, v35
	v_add_f32_e32 v23, 1.0, v23
	v_rcp_f32_e32 v23, v23
	v_add_f32_e32 v35, 1.0, v35
	v_rcp_f32_e32 v35, v35
	v_mul_f32_e32 v23, v186, v23
	v_exp_f32_e32 v23, v23
	s_nop 0
	v_fma_f32 v38, -v23, v23, 1.0
	v_sqrt_f32_e32 v38, v38
	s_nop 0
	v_mul_f32_e32 v35, v35, v38
	v_mul_f32_e32 v35, v61, v35
	v_fmac_f32_e32 v35, v23, v17
	global_store_dword v[28:29], v35, off offset:128
	v_mov_b32_e32 v17, v226
	v_add_f32_e32 v23, v178, v36
	v_exp_f32_e32 v23, v23
	v_add_f32_e32 v36, v177, v40
	v_exp_f32_e32 v36, v36
	v_add_f32_e32 v23, 1.0, v23
	v_rcp_f32_e32 v23, v23
	v_add_f32_e32 v36, 1.0, v36
	v_rcp_f32_e32 v36, v36
	v_mul_f32_e32 v23, v186, v23
	v_exp_f32_e32 v23, v23
	s_nop 0
	v_fma_f32 v38, -v23, v23, 1.0
	v_sqrt_f32_e32 v38, v38
	v_mul_f32_e32 v17, v23, v17
	v_mul_f32_e32 v36, v36, v38
	v_fmac_f32_e32 v17, v58, v36
	global_store_dword v[30:31], v17, off offset:128
	v_mov_b32_e32 v23, v227
	v_add_f32_e32 v36, v178, v37
	v_exp_f32_e32 v36, v36
	v_add_f32_e32 v37, v177, v41
	v_exp_f32_e32 v37, v37
	ds_write_b32 v189, v34 offset:40832
	ds_write_b32 v189, v35 offset:41168
	ds_write_b32 v189, v17 offset:41504
	v_add_f32_e32 v36, 1.0, v36
	v_rcp_f32_e32 v36, v36
	v_add_f32_e32 v37, 1.0, v37
	v_rcp_f32_e32 v37, v37
	v_mul_f32_e32 v36, v186, v36
	v_exp_f32_e32 v36, v36
	s_nop 0
	v_fma_f32 v38, -v36, v36, 1.0
	v_sqrt_f32_e32 v38, v38
	v_mul_f32_e32 v17, v36, v23
	v_mul_f32_e32 v37, v37, v38
	v_fmac_f32_e32 v17, v57, v37
	ds_write_b32 v189, v17 offset:41840
	ds_read_b128 v[34:37], v191 offset:9984
	ds_read_b128 v[38:41], v191 offset:10048
	ds_read_b128 v[42:45], v191 offset:26624
	ds_read_b128 v[46:49], v191 offset:10112
	global_store_dword v[32:33], v17, off offset:128
	v_mov_b32_e32 v17, v228
	s_waitcnt lgkmcnt(3)
	v_mfma_f32_16x16x32_bf16 v[34:37], v[10:13], v[34:37], 0
	ds_read_b128 v[50:53], v191 offset:26752
	s_waitcnt lgkmcnt(3)
	v_mfma_f32_16x16x32_bf16 v[34:37], v[6:9], v[38:41], v[34:37]
	ds_read_b128 v[38:41], v191 offset:26688
	s_waitcnt lgkmcnt(2)
	v_mfma_f32_16x16x32_bf16 v[34:37], v[2:5], v[46:49], v[34:37]
	v_mfma_f32_16x16x32_bf16 v[42:45], v[10:13], v[42:45], 0
	s_waitcnt lgkmcnt(0)
	v_mfma_f32_16x16x32_bf16 v[38:41], v[6:9], v[38:41], v[42:45]
	s_nop 4
	v_add_f32_e32 v23, v176, v34
	v_exp_f32_e32 v23, v23
	v_mfma_f32_16x16x32_bf16 v[38:41], v[2:5], v[50:53], v[38:41]
	ds_read2_b32 v[50:51], v138 offset0:4 offset1:20
	v_add_f32_e32 v23, 1.0, v23
	v_rcp_f32_e32 v23, v23
	ds_read2_b32 v[52:53], v138 offset0:172 offset1:188
	v_mul_f32_e32 v23, v185, v23
	s_nop 2
	v_add_f32_e32 v34, v175, v38
	v_exp_f32_e32 v34, v34
	v_exp_f32_e32 v23, v23
	v_add_f32_e32 v34, 1.0, v34
	v_fma_f32 v38, -v23, v23, 1.0
	v_rcp_f32_e32 v34, v34
	v_sqrt_f32_e32 v38, v38
	s_nop 0
	v_mul_f32_e32 v34, v34, v38
	v_mul_f32_e32 v34, v55, v34
	v_fmac_f32_e32 v34, v17, v23
	global_store_dword v[24:25], v34, off offset:192
	v_mov_b32_e32 v17, v229
	v_add_f32_e32 v23, v176, v35
	v_exp_f32_e32 v23, v23
	v_add_f32_e32 v35, v175, v39
	v_exp_f32_e32 v35, v35
	v_add_f32_e32 v23, 1.0, v23
	v_rcp_f32_e32 v23, v23
	v_add_f32_e32 v35, 1.0, v35
	v_rcp_f32_e32 v35, v35
	v_mul_f32_e32 v23, v185, v23
	v_exp_f32_e32 v23, v23
	s_nop 0
	v_fma_f32 v38, -v23, v23, 1.0
	v_sqrt_f32_e32 v38, v38
	s_nop 0
	v_mul_f32_e32 v35, v35, v38
	s_waitcnt lgkmcnt(1)
; #define LAS __attribute__((address_space(3)))
; template <int PASS, bool SAMP> __device__ __forceinline__ void lru_tile(const Args& a, int z, unsigned char* ws, LAS unsigned char* lds, int n, int row0, int tib0, int lane, int wave, ...
;     ...
;     for (int ct = 0; ct < 5; ++ct) {
;         f32x4 ar = {0.f, 0.f, 0.f, 0.f}, ai = {0.f, 0.f, 0.f, 0.f};
; #pragma unroll
;         for (int j = 0; j < 3; ++j) {
;             const bf16x8 br = *(const LAS bf16x8*)(lds + L2_LW + (ct * 16 + l15) * 208 + (32 * j + 8 * g4) * 2);
;             const bf16x8 bi = *(const LAS bf16x8*)(lds + L2_LW + (80 + ct * 16 + l15) * 208 + (32 * j + 8 * g4) * 2);
;             ar = __builtin_amdgcn_mfma_f32_16x16x32_bf16(af[j], br, ar, 0, 0, 0);
;             ai = __builtin_amdgcn_mfma_f32_16x16x32_bf16(af[j], bi, ai, 0, 0, 0);
;         }
;         const int ch = ct * 16 + l15;
;         float av[4], bv[4];
; #pragma unroll
;         for (int i = 0; i < 4; ++i) {
;             const float r = __builtin_amdgcn_rcpf(1.f + __builtin_amdgcn_exp2f(ar[i] + gba[ct])), gi = __builtin_amdgcn_rcpf(1.f + __builtin_amdgcn_exp2f(ai[i] + gbi[ct]));
;             av[i] = __builtin_amdgcn_exp2f(r * gsp[ct]);
;             bv[i] = __builtin_amdgcn_sqrtf(__builtin_fmaf(-av[i], av[i], 1.f)) * gi * xt[(4 * g4 + i) * L2_TPITCH + ch];
;         }
;         float hv[4];
;         if constexpr (SAMP) {
;             const float* sh = (const float*)a.in[I_SH + z];
; #pragma unroll
;             for (int i = 0; i < 4; ++i) { const int s = row0 - MP + 4 * g4 + i; hv[i] = av[i] * sh[(size_t)s * DRNN + ch0 + ch] + bv[i]; ((float*)a.in[I_OUT + z])[O_H_S + (size_t)s * DRNN + ch0 + ch] = hv[i]; }
	v_mul_f32_e32 v35, v50, v35
	v_fmac_f32_e32 v35, v23, v17
	global_store_dword v[28:29], v35, off offset:192
	v_mov_b32_e32 v17, v230
	v_add_f32_e32 v23, v176, v36
	v_exp_f32_e32 v23, v23
	v_add_f32_e32 v36, v175, v40
	v_exp_f32_e32 v36, v36
	v_add_f32_e32 v23, 1.0, v23
	v_rcp_f32_e32 v23, v23
	v_add_f32_e32 v36, 1.0, v36
	v_rcp_f32_e32 v36, v36
	v_mul_f32_e32 v23, v185, v23
	v_exp_f32_e32 v23, v23
	s_nop 0
	v_fma_f32 v38, -v23, v23, 1.0
	v_sqrt_f32_e32 v38, v38
	v_mul_f32_e32 v17, v23, v17
	v_mul_f32_e32 v36, v36, v38
	v_fmac_f32_e32 v17, v59, v36
	global_store_dword v[30:31], v17, off offset:192
	v_mov_b32_e32 v23, v231
	v_add_f32_e32 v36, v176, v37
	v_exp_f32_e32 v36, v36
	v_add_f32_e32 v37, v175, v41
	v_exp_f32_e32 v37, v37
	ds_write_b32 v189, v34 offset:40896
	ds_write_b32 v189, v35 offset:41232
	ds_write_b32 v189, v17 offset:41568
	v_add_f32_e32 v36, 1.0, v36
	v_rcp_f32_e32 v36, v36
	v_add_f32_e32 v37, 1.0, v37
	v_rcp_f32_e32 v37, v37
	v_mul_f32_e32 v36, v185, v36
	v_exp_f32_e32 v36, v36
	s_nop 0
	v_fma_f32 v38, -v36, v36, 1.0
	v_sqrt_f32_e32 v38, v38
	v_mul_f32_e32 v17, v36, v23
	v_mul_f32_e32 v37, v37, v38
	s_waitcnt lgkmcnt(3)
	v_fmac_f32_e32 v17, v52, v37
	ds_write_b32 v189, v17 offset:41904
	ds_read_b128 v[34:37], v191 offset:13312
	ds_read_b128 v[38:41], v191 offset:13376
	ds_read_b128 v[42:45], v191 offset:29952
	ds_read_b128 v[46:49], v191 offset:13440
	global_store_dword v[32:33], v17, off offset:192
	v_mov_b32_e32 v17, v232
	s_waitcnt lgkmcnt(3)
	v_mfma_f32_16x16x32_bf16 v[34:37], v[10:13], v[34:37], 0
	s_waitcnt lgkmcnt(2)
	v_mfma_f32_16x16x32_bf16 v[34:37], v[6:9], v[38:41], v[34:37]
	ds_read_b128 v[38:41], v191 offset:30016
	s_waitcnt lgkmcnt(2)
	v_mfma_f32_16x16x32_bf16 v[10:13], v[10:13], v[42:45], 0
	ds_read_b128 v[42:45], v191 offset:30080
	s_waitcnt lgkmcnt(1)
	v_mfma_f32_16x16x32_bf16 v[6:9], v[6:9], v[38:41], v[10:13]
	v_mfma_f32_16x16x32_bf16 v[10:13], v[2:5], v[46:49], v[34:37]
	s_waitcnt lgkmcnt(0)
	v_mfma_f32_16x16x32_bf16 v[2:5], v[2:5], v[42:45], v[6:9]
	s_nop 5
	v_add_f32_e32 v10, v174, v10
	v_exp_f32_e32 v10, v10
	v_add_f32_e32 v2, v1, v2
	v_exp_f32_e32 v2, v2
	v_add_f32_e32 v3, v1, v3
	v_add_f32_e32 v10, 1.0, v10
	v_rcp_f32_e32 v10, v10
	v_add_f32_e32 v2, 1.0, v2
	v_rcp_f32_e32 v2, v2
	v_exp_f32_e32 v3, v3
	v_mul_f32_e32 v6, v183, v10
	v_exp_f32_e32 v6, v6
	v_add_f32_e32 v4, v1, v4
	v_add_f32_e32 v3, 1.0, v3
	v_rcp_f32_e32 v3, v3
	v_fma_f32 v7, -v6, v6, 1.0
	v_sqrt_f32_e32 v7, v7
	v_exp_f32_e32 v4, v4
	v_add_f32_e32 v1, v1, v5
	v_exp_f32_e32 v1, v1
	v_mul_f32_e32 v2, v2, v7
	v_mul_f32_e32 v7, v16, v2
	v_add_f32_e32 v4, 1.0, v4
	v_rcp_f32_e32 v4, v4
	v_add_f32_e32 v1, 1.0, v1
	v_rcp_f32_e32 v1, v1
	v_fmac_f32_e32 v7, v17, v6
	global_store_dword v[24:25], v7, off offset:256
	v_mov_b32_e32 v2, v233
	v_add_f32_e32 v6, v174, v11
	v_exp_f32_e32 v6, v6
	s_nop 0
	v_add_f32_e32 v6, 1.0, v6
	v_rcp_f32_e32 v6, v6
	s_nop 0
	v_mul_f32_e32 v6, v183, v6
	v_exp_f32_e32 v6, v6
	s_nop 0
	v_fma_f32 v8, -v6, v6, 1.0
	v_sqrt_f32_e32 v8, v8
	s_nop 0
	v_mul_f32_e32 v3, v3, v8
	v_mul_f32_e32 v8, v51, v3
	v_add_f32_e32 v3, v174, v12
	v_exp_f32_e32 v3, v3
	v_fmac_f32_e32 v8, v6, v2
	global_store_dword v[28:29], v8, off offset:256
	v_mov_b32_e32 v2, v234
	v_add_f32_e32 v3, 1.0, v3
	v_rcp_f32_e32 v3, v3
	s_nop 0
	v_mul_f32_e32 v3, v183, v3
	v_exp_f32_e32 v3, v3
	s_nop 0
	v_fma_f32 v6, -v3, v3, 1.0
	v_sqrt_f32_e32 v6, v6
	s_nop 0
	v_mul_f32_e32 v4, v4, v6
	v_mul_f32_e32 v6, v3, v2
	v_fmac_f32_e32 v6, v22, v4
	global_store_dword v[30:31], v6, off offset:256
	v_mov_b32_e32 v4, v235
	v_add_f32_e32 v2, v174, v13
	v_exp_f32_e32 v2, v2
	ds_write_b32 v189, v7 offset:40960
	ds_write_b32 v189, v8 offset:41296
	ds_write_b32 v189, v6 offset:41632
	v_add_f32_e32 v2, 1.0, v2
	v_rcp_f32_e32 v2, v2
	s_nop 0
	v_mul_f32_e32 v2, v183, v2
	v_exp_f32_e32 v5, v2
	s_nop 0
	v_fma_f32 v2, -v5, v5, 1.0
	v_sqrt_f32_e32 v9, v2
	v_mov_b64_e32 v[2:3], s[44:45]
	v_mad_u64_u32 v[2:3], s[14:15], v68, s72, v[2:3]
	v_mul_f32_e32 v1, v1, v9
	v_lshl_add_u64 v[2:3], v[2:3], 0, s[0:1]
	v_lshl_add_u64 v[2:3], v[154:155], 1, v[2:3]
	v_mul_f32_e32 v4, v5, v4
	v_fmac_f32_e32 v4, v53, v1
	global_store_dword v[32:33], v4, off offset:256
	ds_write_b32 v189, v4 offset:41968
	s_waitcnt lgkmcnt(0)
	s_and_saveexec_b64 s[0:1], s[8:9]
	s_cbranch_execnz .LBB0_1150
	s_or_b64 exec, exec, s[0:1]
	s_and_saveexec_b64 s[0:1], s[10:11]
	s_cbranch_execnz .LBB0_1151

; __device__ __forceinline__ float bflo(unsigned w) { return __uint_as_float(w << 16); }
; __device__ __forceinline__ float bfhi(unsigned w) { return __uint_as_float(w & 0xffff0000u); }
; __device__ __forceinline__ unsigned pk2(float lo, float hi) { f32x2 v = {lo, hi}; bf16x2_t b = __builtin_convertvector(v, bf16x2_t); return __builtin_bit_cast(unsigned, b); }
;     __device__ __forceinline__ void fused(f32x4 (&acc)[2][2][4][2], const Unit& u, int wr, int wc, int fr, int fq, LAS unsigned char* lds, int wid, int lane) const {
;     ...
; #pragma unroll
;         for (int bj = 0; bj < 2; ++bj) {
;             const int col = u.pn * BM + bj * HALF + wc * 32 + 8 * fq;
;             const f32x4 g0 = *(const f32x4*)(gpost + col), g1 = *(const f32x4*)(gpost + col + 4);
; #pragma unroll
;             for (int ai = 0; ai < 2; ++ai)
; #pragma unroll
;                 for (int m = 0; m < 4; ++m) {
;                     const int rl = ai * HALF + wr * 64 + m * 16 + fr; const size_t off = (size_t)(u.pm * BM + rl) * 1024 + col; const float r = S[rl];
;                     f32x4 x0, x1;
;                     if constexpr (SRC == 0) { x0 = *(const f32x4*)(xin + off); x1 = *(const f32x4*)(xin + off + 4); }
;                     else { const u32x4 w = *(const u32x4*)((SRC == 1 ? XR : XN) + off); x0 = (f32x4){bflo(w.x), bfhi(w.x), bflo(w.y), bfhi(w.y)}; x1 = (f32x4){bflo(w.z), bfhi(w.z), bflo(w.w), bfhi(w.w)}; }
;                     x0 = x0 + acc[ai][bj][m][0] * g0 * r; x1 = x1 + acc[ai][bj][m][1] * g1 * r;
;                     acc[ai][bj][m][0] = x0; acc[ai][bj][m][1] = x1;
;                     if constexpr (NEXT == 0) { *(f32x4*)(Y + off) = x0; *(f32x4*)(Y + off + 4) = x1; }
;                     else { u32x4 w; w.x = pk2(x0[0], x0[1]); w.y = pk2(x0[2], x0[3]); w.z = pk2(x1[0], x1[1]); w.w = pk2(x1[2], x1[3]); *(u32x4*)((NEXT == 1 ? XR : XN) + off) = w; }
;                 }
;         }
.LBB0_1958:
	s_or_b64 exec, exec, s[4:5]
	s_add_u32 s4, s0, 0xdc00000
	s_addc_u32 s5, s1, 0
	s_add_u32 s2, s0, 0x4000000
	s_addc_u32 s3, s1, 0
	s_lshl_b32 s6, s34, 5
	s_lshl_b32 s7, s12, 8
	v_lshrrev_b32_e32 v128, 1, v141
	s_or_b32 s6, s7, s6
	v_lshl_add_u32 v148, s10, 8, v152
	v_and_or_b32 v144, v128, 24, s6
	v_ashrrev_i32_e32 v149, 31, v148
	v_ashrrev_i32_e32 v145, 31, v144
	v_lshlrev_b64 v[146:147], 10, v[148:149]
	v_lshl_add_u64 v[136:137], v[146:147], 0, v[144:145]
	v_lshlrev_b64 v[150:151], 1, v[136:137]
	s_waitcnt vmcnt(0) lgkmcnt(0)
	s_barrier
	v_lshl_add_u64 v[142:143], v[144:145], 2, s[8:9]
	v_lshl_add_u64 v[136:137], s[4:5], 0, v[150:151]
	global_load_dwordx4 v[128:131], v[142:143], off offset:16
	global_load_dwordx4 v[132:135], v[142:143], off
	v_lshl_add_u32 v141, v152, 2, 0
	s_mov_b32 s98, 0x8000
	s_mov_b32 s99, 0
	v_lshl_add_u64 v[228:229], v[136:137], 0, s[98:99]
	global_load_dwordx4 v[166:169], v[228:229], off
	s_mov_b32 s98, 0x10000
	s_mov_b32 s99, 0
	v_lshl_add_u64 v[228:229], v[136:137], 0, s[98:99]
	global_load_dwordx4 v[170:173], v[228:229], off
	s_mov_b32 s98, 0x18000
	s_mov_b32 s99, 0
	v_lshl_add_u64 v[228:229], v[136:137], 0, s[98:99]
	global_load_dwordx4 v[174:177], v[228:229], off
	s_mov_b32 s98, 0x40000
	s_mov_b32 s99, 0
	v_lshl_add_u64 v[228:229], v[136:137], 0, s[98:99]
	global_load_dwordx4 v[178:181], v[228:229], off
	s_mov_b32 s98, 0x48000
	s_mov_b32 s99, 0
	v_lshl_add_u64 v[228:229], v[136:137], 0, s[98:99]
	global_load_dwordx4 v[182:185], v[228:229], off
	s_mov_b32 s98, 0x50000
	s_mov_b32 s99, 0
	v_lshl_add_u64 v[228:229], v[136:137], 0, s[98:99]
	global_load_dwordx4 v[186:189], v[228:229], off
	s_mov_b32 s98, 0x58000
	s_mov_b32 s99, 0
	v_lshl_add_u64 v[228:229], v[136:137], 0, s[98:99]
	global_load_dwordx4 v[190:193], v[228:229], off
	global_load_dwordx4 v[194:197], v[136:137], off offset:256
	s_mov_b32 s98, 0x8000
	s_mov_b32 s99, 0
	v_lshl_add_u64 v[228:229], v[136:137], 0, s[98:99]
	global_load_dwordx4 v[198:201], v[228:229], off offset:256
	s_mov_b32 s98, 0x10000
	s_mov_b32 s99, 0
	v_lshl_add_u64 v[228:229], v[136:137], 0, s[98:99]
	global_load_dwordx4 v[202:205], v[228:229], off offset:256
	s_mov_b32 s98, 0x18000
	s_mov_b32 s99, 0
	v_lshl_add_u64 v[228:229], v[136:137], 0, s[98:99]
	global_load_dwordx4 v[206:209], v[228:229], off offset:256
	s_mov_b32 s98, 0x40000
	s_mov_b32 s99, 0
	v_lshl_add_u64 v[228:229], v[136:137], 0, s[98:99]
	global_load_dwordx4 v[210:213], v[228:229], off offset:256
	s_mov_b32 s98, 0x48000
	s_mov_b32 s99, 0
	v_lshl_add_u64 v[228:229], v[136:137], 0, s[98:99]
	global_load_dwordx4 v[214:217], v[228:229], off offset:256
	s_mov_b32 s98, 0x50000
	s_mov_b32 s99, 0
	v_lshl_add_u64 v[228:229], v[136:137], 0, s[98:99]
	global_load_dwordx4 v[220:223], v[228:229], off offset:256
	s_mov_b32 s98, 0x58000
	s_mov_b32 s99, 0
	v_lshl_add_u64 v[228:229], v[136:137], 0, s[98:99]
	global_load_dwordx4 v[224:227], v[228:229], off offset:256
	global_load_dwordx4 v[136:139], v[136:137], off
	ds_read_b32 v152, v141 offset:4096
	s_waitcnt vmcnt(0)
	ds_read_b32 v156, v141 offset:4800
	v_add_u32_e32 v154, 16, v148
	v_ashrrev_i32_e32 v155, 31, v154
	v_lshlrev_b64 v[154:155], 10, v[154:155]
	v_lshl_add_u64 v[158:159], v[154:155], 0, v[144:145]
	v_lshlrev_b64 v[158:159], 1, v[158:159]
	v_lshl_add_u64 v[150:151], s[2:3], 0, v[150:151]
	v_lshl_add_u64 v[160:161], s[4:5], 0, v[158:159]
	v_add_u32_e32 v141, 0x1000, v141
	v_pk_mul_f32 v[122:123], v[122:123], v[130:131]
	v_pk_mul_f32 v[126:127], v[126:127], v[134:135]
	v_pk_mul_f32 v[124:125], v[124:125], v[132:133]
	v_pk_mul_f32 v[120:121], v[120:121], v[128:129]
	v_lshlrev_b32_e32 v162, 16, v136
	v_and_b32_e32 v163, 0xffff0000, v136
	v_lshlrev_b32_e32 v136, 16, v137
	v_and_b32_e32 v137, 0xffff0000, v137
	v_lshlrev_b32_e32 v164, 16, v138
	v_and_b32_e32 v165, 0xffff0000, v138
	v_lshlrev_b32_e32 v138, 16, v139
	v_and_b32_e32 v139, 0xffff0000, v139
	s_waitcnt lgkmcnt(1)
	v_pk_fma_f32 v[126:127], v[126:127], v[152:153], v[136:137] op_sel_hi:[1,0,1]
	v_pk_fma_f32 v[124:125], v[124:125], v[152:153], v[162:163] op_sel_hi:[1,0,1]
	v_pk_fma_f32 v[136:137], v[122:123], v[152:153], v[138:139] op_sel_hi:[1,0,1]
	v_pk_fma_f32 v[122:123], v[120:121], v[152:153], v[164:165] op_sel_hi:[1,0,1]
	v_cvt_pk_bf16_f32 v120, v124, v125
	v_cvt_pk_bf16_f32 v121, v126, v127
	v_cvt_pk_bf16_f32 v122, v122, v123
	v_cvt_pk_bf16_f32 v123, v136, v137
	global_store_dwordx4 v[150:151], v[120:123], off
	s_nop 1
	v_mov_b64_e32 v[120:121], v[166:167]
	v_mov_b64_e32 v[122:123], v[168:169]
	ds_read2_b32 v[124:125], v141 offset1:16
	v_add_u32_e32 v126, 32, v148
	v_ashrrev_i32_e32 v127, 31, v126
	v_lshlrev_b64 v[126:127], 10, v[126:127]
	v_lshl_add_u64 v[150:151], s[2:3], 0, v[158:159]
	s_waitcnt lgkmcnt(0)
; __device__ __forceinline__ float bflo(unsigned w) { return __uint_as_float(w << 16); }
; __device__ __forceinline__ float bfhi(unsigned w) { return __uint_as_float(w & 0xffff0000u); }
; __device__ __forceinline__ unsigned pk2(float lo, float hi) { f32x2 v = {lo, hi}; bf16x2_t b = __builtin_convertvector(v, bf16x2_t); return __builtin_bit_cast(unsigned, b); }
;     __device__ __forceinline__ void fused(f32x4 (&acc)[2][2][4][2], const Unit& u, int wr, int wc, int fr, int fq, LAS unsigned char* lds, int wid, int lane) const {
;     ...
;             for (int ai = 0; ai < 2; ++ai)
; #pragma unroll
;                 for (int m = 0; m < 4; ++m) {
;                     const int rl = ai * HALF + wr * 64 + m * 16 + fr; const size_t off = (size_t)(u.pm * BM + rl) * 1024 + col; const float r = S[rl];
;                     f32x4 x0, x1;
;                     if constexpr (SRC == 0) { x0 = *(const f32x4*)(xin + off); x1 = *(const f32x4*)(xin + off + 4); }
;                     else { const u32x4 w = *(const u32x4*)((SRC == 1 ? XR : XN) + off); x0 = (f32x4){bflo(w.x), bfhi(w.x), bflo(w.y), bfhi(w.y)}; x1 = (f32x4){bflo(w.z), bfhi(w.z), bflo(w.w), bfhi(w.w)}; }
;                     x0 = x0 + acc[ai][bj][m][0] * g0 * r; x1 = x1 + acc[ai][bj][m][1] * g1 * r;
;                     acc[ai][bj][m][0] = x0; acc[ai][bj][m][1] = x1;
;                     if constexpr (NEXT == 0) { *(f32x4*)(Y + off) = x0; *(f32x4*)(Y + off + 4) = x1; }
;                     else { u32x4 w; w.x = pk2(x0[0], x0[1]); w.y = pk2(x0[2], x0[3]); w.z = pk2(x1[0], x1[1]); w.w = pk2(x1[2], x1[3]); *(u32x4*)((NEXT == 1 ? XR : XN) + off) = w; }
;                 }
	v_mov_b32_e32 v136, v125
	v_pk_mul_f32 v[118:119], v[118:119], v[134:135]
	v_pk_mul_f32 v[116:117], v[116:117], v[132:133]
	v_pk_mul_f32 v[114:115], v[114:115], v[130:131]
	v_pk_mul_f32 v[112:113], v[112:113], v[128:129]
	v_lshl_add_u64 v[138:139], v[126:127], 0, v[144:145]
	v_lshlrev_b64 v[138:139], 1, v[138:139]
	v_lshl_add_u64 v[152:153], s[4:5], 0, v[138:139]
	v_pk_mul_f32 v[110:111], v[110:111], v[134:135]
	v_pk_mul_f32 v[108:109], v[108:109], v[132:133]
	v_pk_mul_f32 v[106:107], v[106:107], v[130:131]
	v_pk_mul_f32 v[104:105], v[104:105], v[128:129]
	v_pk_mul_f32 v[102:103], v[102:103], v[134:135]
	v_pk_mul_f32 v[100:101], v[100:101], v[132:133]
	v_pk_mul_f32 v[98:99], v[98:99], v[130:131]
	v_pk_mul_f32 v[96:97], v[96:97], v[128:129]
	v_pk_mul_f32 v[94:95], v[94:95], v[134:135]
	v_pk_mul_f32 v[92:93], v[92:93], v[132:133]
	v_pk_mul_f32 v[90:91], v[90:91], v[130:131]
	v_pk_mul_f32 v[88:89], v[88:89], v[128:129]
	v_pk_mul_f32 v[86:87], v[86:87], v[134:135]
	v_pk_mul_f32 v[84:85], v[84:85], v[132:133]
	v_pk_mul_f32 v[82:83], v[82:83], v[130:131]
	v_pk_mul_f32 v[80:81], v[80:81], v[128:129]
	v_pk_mul_f32 v[70:71], v[70:71], v[134:135]
	v_pk_mul_f32 v[68:69], v[68:69], v[132:133]
	v_pk_mul_f32 v[62:63], v[62:63], v[130:131]
	v_pk_mul_f32 v[60:61], v[60:61], v[128:129]
	v_pk_mul_f32 v[54:55], v[54:55], v[134:135]
	v_pk_mul_f32 v[52:53], v[52:53], v[132:133]
	v_pk_mul_f32 v[46:47], v[46:47], v[130:131]
	v_pk_mul_f32 v[44:45], v[44:45], v[128:129]
	v_lshlrev_b32_e32 v158, 16, v120
	v_and_b32_e32 v159, 0xffff0000, v120
	v_lshlrev_b32_e32 v120, 16, v121
	v_and_b32_e32 v121, 0xffff0000, v121
	v_lshlrev_b32_e32 v160, 16, v122
	v_and_b32_e32 v161, 0xffff0000, v122
	v_lshlrev_b32_e32 v122, 16, v123
	v_and_b32_e32 v123, 0xffff0000, v123
	v_pk_fma_f32 v[118:119], v[118:119], v[136:137], v[120:121] op_sel_hi:[1,0,1]
	v_pk_fma_f32 v[116:117], v[116:117], v[136:137], v[158:159] op_sel_hi:[1,0,1]
	v_pk_fma_f32 v[120:121], v[114:115], v[136:137], v[122:123] op_sel_hi:[1,0,1]
	v_pk_fma_f32 v[114:115], v[112:113], v[136:137], v[160:161] op_sel_hi:[1,0,1]
	v_cvt_pk_bf16_f32 v112, v116, v117
	v_cvt_pk_bf16_f32 v113, v118, v119
	v_cvt_pk_bf16_f32 v114, v114, v115
	v_cvt_pk_bf16_f32 v115, v120, v121
	global_store_dwordx4 v[150:151], v[112:115], off
	s_nop 1
	v_mov_b64_e32 v[112:113], v[170:171]
	v_mov_b64_e32 v[114:115], v[172:173]
	ds_read2_b32 v[116:117], v141 offset0:16 offset1:32
	v_add_u32_e32 v118, 48, v148
	v_ashrrev_i32_e32 v119, 31, v118
	v_lshlrev_b64 v[118:119], 10, v[118:119]
	v_lshl_add_u64 v[122:123], v[118:119], 0, v[144:145]
	s_waitcnt lgkmcnt(0)
	v_mov_b32_e32 v120, v117
	v_lshlrev_b64 v[122:123], 1, v[122:123]
	v_lshl_add_u64 v[136:137], s[2:3], 0, v[138:139]
	v_lshl_add_u64 v[138:139], s[4:5], 0, v[122:123]
	v_lshlrev_b32_e32 v150, 16, v112
	v_and_b32_e32 v151, 0xffff0000, v112
	v_lshlrev_b32_e32 v112, 16, v113
	v_and_b32_e32 v113, 0xffff0000, v113
	v_lshlrev_b32_e32 v152, 16, v114
	v_and_b32_e32 v153, 0xffff0000, v114
	v_lshlrev_b32_e32 v114, 16, v115
	v_and_b32_e32 v115, 0xffff0000, v115
	v_pk_fma_f32 v[110:111], v[110:111], v[120:121], v[112:113] op_sel_hi:[1,0,1]
	v_pk_fma_f32 v[108:109], v[108:109], v[120:121], v[150:151] op_sel_hi:[1,0,1]
	v_pk_fma_f32 v[112:113], v[106:107], v[120:121], v[114:115] op_sel_hi:[1,0,1]
	v_pk_fma_f32 v[106:107], v[104:105], v[120:121], v[152:153] op_sel_hi:[1,0,1]
	v_cvt_pk_bf16_f32 v104, v108, v109
	v_cvt_pk_bf16_f32 v105, v110, v111
	v_cvt_pk_bf16_f32 v106, v106, v107
	v_cvt_pk_bf16_f32 v107, v112, v113
	global_store_dwordx4 v[136:137], v[104:107], off
	s_nop 1
	v_mov_b64_e32 v[104:105], v[174:175]
	v_mov_b64_e32 v[106:107], v[176:177]
	ds_read2_b32 v[108:109], v141 offset0:32 offset1:48
	v_add_u32_e32 v110, 0x80, v148
	v_ashrrev_i32_e32 v111, 31, v110
	v_lshlrev_b64 v[110:111], 10, v[110:111]
	v_lshl_add_u64 v[114:115], v[110:111], 0, v[144:145]
	s_waitcnt lgkmcnt(0)
	v_mov_b32_e32 v112, v109
	v_lshlrev_b64 v[114:115], 1, v[114:115]
	v_lshl_add_u64 v[120:121], s[2:3], 0, v[122:123]
	v_lshl_add_u64 v[122:123], s[4:5], 0, v[114:115]
	v_lshlrev_b32_e32 v136, 16, v104
	v_and_b32_e32 v137, 0xffff0000, v104
	v_lshlrev_b32_e32 v104, 16, v105
	v_and_b32_e32 v105, 0xffff0000, v105
	v_lshlrev_b32_e32 v138, 16, v106
	v_and_b32_e32 v139, 0xffff0000, v106
	v_lshlrev_b32_e32 v106, 16, v107
	v_and_b32_e32 v107, 0xffff0000, v107
	v_pk_fma_f32 v[102:103], v[102:103], v[112:113], v[104:105] op_sel_hi:[1,0,1]
	v_pk_fma_f32 v[100:101], v[100:101], v[112:113], v[136:137] op_sel_hi:[1,0,1]
	v_pk_fma_f32 v[104:105], v[98:99], v[112:113], v[106:107] op_sel_hi:[1,0,1]
	v_pk_fma_f32 v[98:99], v[96:97], v[112:113], v[138:139] op_sel_hi:[1,0,1]
	v_cvt_pk_bf16_f32 v96, v100, v101
	v_cvt_pk_bf16_f32 v97, v102, v103
	v_cvt_pk_bf16_f32 v98, v98, v99
	v_cvt_pk_bf16_f32 v99, v104, v105
	global_store_dwordx4 v[120:121], v[96:99], off
	s_nop 1
	v_mov_b64_e32 v[96:97], v[178:179]
	v_mov_b64_e32 v[98:99], v[180:181]
	ds_read2_b32 v[100:101], v141 offset0:48 offset1:128
	v_add_u32_e32 v102, 0x90, v148
	v_ashrrev_i32_e32 v103, 31, v102
	v_lshlrev_b64 v[102:103], 10, v[102:103]
	v_lshl_add_u64 v[106:107], v[102:103], 0, v[144:145]
	s_waitcnt lgkmcnt(0)
; __device__ __forceinline__ float bflo(unsigned w) { return __uint_as_float(w << 16); }
; __device__ __forceinline__ float bfhi(unsigned w) { return __uint_as_float(w & 0xffff0000u); }
; __device__ __forceinline__ unsigned pk2(float lo, float hi) { f32x2 v = {lo, hi}; bf16x2_t b = __builtin_convertvector(v, bf16x2_t); return __builtin_bit_cast(unsigned, b); }
;     __device__ __forceinline__ void fused(f32x4 (&acc)[2][2][4][2], const Unit& u, int wr, int wc, int fr, int fq, LAS unsigned char* lds, int wid, int lane) const {
;     ...
; #pragma unroll
;         for (int bj = 0; bj < 2; ++bj) {
;             const int col = u.pn * BM + bj * HALF + wc * 32 + 8 * fq;
;             const f32x4 g0 = *(const f32x4*)(gpost + col), g1 = *(const f32x4*)(gpost + col + 4);
;     ...
;             for (int ai = 0; ai < 2; ++ai)
; #pragma unroll
;                 for (int m = 0; m < 4; ++m) {
;                     const int rl = ai * HALF + wr * 64 + m * 16 + fr; const size_t off = (size_t)(u.pm * BM + rl) * 1024 + col; const float r = S[rl];
;                     f32x4 x0, x1;
;                     if constexpr (SRC == 0) { x0 = *(const f32x4*)(xin + off); x1 = *(const f32x4*)(xin + off + 4); }
;                     else { const u32x4 w = *(const u32x4*)((SRC == 1 ? XR : XN) + off); x0 = (f32x4){bflo(w.x), bfhi(w.x), bflo(w.y), bfhi(w.y)}; x1 = (f32x4){bflo(w.z), bfhi(w.z), bflo(w.w), bfhi(w.w)}; }
;                     x0 = x0 + acc[ai][bj][m][0] * g0 * r; x1 = x1 + acc[ai][bj][m][1] * g1 * r;
;                     acc[ai][bj][m][0] = x0; acc[ai][bj][m][1] = x1;
;                     if constexpr (NEXT == 0) { *(f32x4*)(Y + off) = x0; *(f32x4*)(Y + off + 4) = x1; }
;                     else { u32x4 w; w.x = pk2(x0[0], x0[1]); w.y = pk2(x0[2], x0[3]); w.z = pk2(x1[0], x1[1]); w.w = pk2(x1[2], x1[3]); *(u32x4*)((NEXT == 1 ? XR : XN) + off) = w; }
;                 }
	v_mov_b32_e32 v104, v101
	v_lshlrev_b64 v[106:107], 1, v[106:107]
	v_lshl_add_u64 v[112:113], s[2:3], 0, v[114:115]
	v_lshl_add_u64 v[114:115], s[4:5], 0, v[106:107]
	v_lshlrev_b32_e32 v120, 16, v96
	v_and_b32_e32 v121, 0xffff0000, v96
	v_lshlrev_b32_e32 v96, 16, v97
	v_and_b32_e32 v97, 0xffff0000, v97
	v_lshlrev_b32_e32 v122, 16, v98
	v_and_b32_e32 v123, 0xffff0000, v98
	v_lshlrev_b32_e32 v98, 16, v99
	v_and_b32_e32 v99, 0xffff0000, v99
	v_pk_fma_f32 v[94:95], v[94:95], v[104:105], v[96:97] op_sel_hi:[1,0,1]
	v_pk_fma_f32 v[92:93], v[92:93], v[104:105], v[120:121] op_sel_hi:[1,0,1]
	v_pk_fma_f32 v[96:97], v[90:91], v[104:105], v[98:99] op_sel_hi:[1,0,1]
	v_pk_fma_f32 v[90:91], v[88:89], v[104:105], v[122:123] op_sel_hi:[1,0,1]
	v_cvt_pk_bf16_f32 v88, v92, v93
	v_cvt_pk_bf16_f32 v89, v94, v95
	v_cvt_pk_bf16_f32 v90, v90, v91
	v_cvt_pk_bf16_f32 v91, v96, v97
	global_store_dwordx4 v[112:113], v[88:91], off
	s_nop 1
	v_mov_b64_e32 v[88:89], v[182:183]
	v_mov_b64_e32 v[90:91], v[184:185]
	ds_read2_b32 v[92:93], v141 offset0:128 offset1:144
	v_add_u32_e32 v94, 0xa0, v148
	v_ashrrev_i32_e32 v95, 31, v94
	v_lshlrev_b64 v[94:95], 10, v[94:95]
	v_lshl_add_u64 v[98:99], v[94:95], 0, v[144:145]
	s_waitcnt lgkmcnt(0)
	v_mov_b32_e32 v96, v93
	v_lshlrev_b64 v[98:99], 1, v[98:99]
	v_lshl_add_u64 v[104:105], s[2:3], 0, v[106:107]
	v_lshl_add_u64 v[106:107], s[4:5], 0, v[98:99]
	v_lshlrev_b32_e32 v112, 16, v88
	v_and_b32_e32 v113, 0xffff0000, v88
	v_lshlrev_b32_e32 v88, 16, v89
	v_and_b32_e32 v89, 0xffff0000, v89
	v_lshlrev_b32_e32 v114, 16, v90
	v_and_b32_e32 v115, 0xffff0000, v90
	v_lshlrev_b32_e32 v90, 16, v91
	v_and_b32_e32 v91, 0xffff0000, v91
	v_pk_fma_f32 v[86:87], v[86:87], v[96:97], v[88:89] op_sel_hi:[1,0,1]
	v_pk_fma_f32 v[84:85], v[84:85], v[96:97], v[112:113] op_sel_hi:[1,0,1]
	v_pk_fma_f32 v[88:89], v[82:83], v[96:97], v[90:91] op_sel_hi:[1,0,1]
	v_pk_fma_f32 v[82:83], v[80:81], v[96:97], v[114:115] op_sel_hi:[1,0,1]
	v_cvt_pk_bf16_f32 v80, v84, v85
	v_cvt_pk_bf16_f32 v81, v86, v87
	v_cvt_pk_bf16_f32 v82, v82, v83
	v_cvt_pk_bf16_f32 v83, v88, v89
	global_store_dwordx4 v[104:105], v[80:83], off
	s_nop 1
	v_mov_b64_e32 v[80:81], v[186:187]
	v_mov_b64_e32 v[82:83], v[188:189]
	ds_read2_b32 v[84:85], v141 offset0:144 offset1:160
	v_add_u32_e32 v86, 0xb0, v148
	v_ashrrev_i32_e32 v87, 31, v86
	v_lshlrev_b64 v[86:87], 10, v[86:87]
	v_lshl_add_u64 v[90:91], v[86:87], 0, v[144:145]
	s_waitcnt lgkmcnt(0)
	v_mov_b32_e32 v88, v85
	v_lshlrev_b64 v[90:91], 1, v[90:91]
	v_lshl_add_u64 v[96:97], s[2:3], 0, v[98:99]
	v_lshl_add_u64 v[98:99], s[4:5], 0, v[90:91]
	v_lshlrev_b32_e32 v104, 16, v80
	v_and_b32_e32 v105, 0xffff0000, v80
	v_lshlrev_b32_e32 v80, 16, v81
	v_and_b32_e32 v81, 0xffff0000, v81
	v_lshlrev_b32_e32 v106, 16, v82
	v_and_b32_e32 v107, 0xffff0000, v82
	v_lshlrev_b32_e32 v82, 16, v83
	v_and_b32_e32 v83, 0xffff0000, v83
	v_pk_fma_f32 v[70:71], v[70:71], v[88:89], v[80:81] op_sel_hi:[1,0,1]
	v_pk_fma_f32 v[68:69], v[68:69], v[88:89], v[104:105] op_sel_hi:[1,0,1]
	v_pk_fma_f32 v[80:81], v[62:63], v[88:89], v[82:83] op_sel_hi:[1,0,1]
	v_pk_fma_f32 v[62:63], v[60:61], v[88:89], v[106:107] op_sel_hi:[1,0,1]
	v_cvt_pk_bf16_f32 v60, v68, v69
	v_cvt_pk_bf16_f32 v61, v70, v71
	v_cvt_pk_bf16_f32 v62, v62, v63
	v_cvt_pk_bf16_f32 v63, v80, v81
	global_store_dwordx4 v[96:97], v[60:63], off
	s_nop 1
	v_mov_b64_e32 v[60:61], v[190:191]
	v_mov_b64_e32 v[62:63], v[192:193]
	ds_read2_b32 v[68:69], v141 offset0:160 offset1:176
	v_or_b32_e32 v70, 0x80, v144
	v_ashrrev_i32_e32 v71, 31, v70
	v_lshl_add_u64 v[82:83], v[146:147], 0, v[70:71]
	v_lshl_add_u64 v[88:89], s[2:3], 0, v[90:91]
	s_waitcnt lgkmcnt(0)
	v_mov_b32_e32 v80, v69
	v_lshlrev_b64 v[82:83], 1, v[82:83]
	v_lshl_add_u64 v[90:91], s[4:5], 0, v[82:83]
	v_lshl_add_u64 v[82:83], s[2:3], 0, v[82:83]
	v_lshlrev_b32_e32 v96, 16, v60
	v_and_b32_e32 v97, 0xffff0000, v60
	v_lshlrev_b32_e32 v60, 16, v61
	v_and_b32_e32 v61, 0xffff0000, v61
	v_lshlrev_b32_e32 v98, 16, v62
	v_and_b32_e32 v99, 0xffff0000, v62
	v_lshlrev_b32_e32 v62, 16, v63
	v_and_b32_e32 v63, 0xffff0000, v63
	v_pk_fma_f32 v[54:55], v[54:55], v[80:81], v[60:61] op_sel_hi:[1,0,1]
	v_pk_fma_f32 v[52:53], v[52:53], v[80:81], v[96:97] op_sel_hi:[1,0,1]
	v_pk_fma_f32 v[60:61], v[46:47], v[80:81], v[62:63] op_sel_hi:[1,0,1]
	v_pk_fma_f32 v[46:47], v[44:45], v[80:81], v[98:99] op_sel_hi:[1,0,1]
	v_cvt_pk_bf16_f32 v44, v52, v53
	v_cvt_pk_bf16_f32 v45, v54, v55
	v_cvt_pk_bf16_f32 v46, v46, v47
	v_cvt_pk_bf16_f32 v47, v60, v61
	global_store_dwordx4 v[88:89], v[44:47], off
	s_nop 1
	v_mov_b64_e32 v[44:45], v[194:195]
	v_mov_b64_e32 v[46:47], v[196:197]
	s_nop 0
	global_load_dwordx4 v[52:55], v[142:143], off offset:512
	global_load_dwordx4 v[60:63], v[142:143], off offset:528
	v_lshl_add_u64 v[80:81], v[154:155], 0, v[70:71]
	v_lshlrev_b64 v[80:81], 1, v[80:81]
	v_lshl_add_u64 v[88:89], s[4:5], 0, v[80:81]
	v_lshlrev_b32_e32 v90, 16, v44
	v_and_b32_e32 v91, 0xffff0000, v44
	v_lshlrev_b32_e32 v44, 16, v45
	v_and_b32_e32 v45, 0xffff0000, v45
	v_lshlrev_b32_e32 v96, 16, v46
	v_and_b32_e32 v97, 0xffff0000, v46
	v_lshlrev_b32_e32 v46, 16, v47
	v_and_b32_e32 v47, 0xffff0000, v47
	s_waitcnt vmcnt(1)
	v_pk_mul_f32 v[78:79], v[78:79], v[54:55]
	v_pk_mul_f32 v[76:77], v[76:77], v[52:53]
	s_waitcnt vmcnt(0)
; __device__ __forceinline__ float bflo(unsigned w) { return __uint_as_float(w << 16); }
; __device__ __forceinline__ float bfhi(unsigned w) { return __uint_as_float(w & 0xffff0000u); }
; __device__ __forceinline__ unsigned pk2(float lo, float hi) { f32x2 v = {lo, hi}; bf16x2_t b = __builtin_convertvector(v, bf16x2_t); return __builtin_bit_cast(unsigned, b); }
;     __device__ __forceinline__ void fused(f32x4 (&acc)[2][2][4][2], const Unit& u, int wr, int wc, int fr, int fq, LAS unsigned char* lds, int wid, int lane) const {
;     ...
;             for (int ai = 0; ai < 2; ++ai)
; #pragma unroll
;                 for (int m = 0; m < 4; ++m) {
;                     const int rl = ai * HALF + wr * 64 + m * 16 + fr; const size_t off = (size_t)(u.pm * BM + rl) * 1024 + col; const float r = S[rl];
;                     f32x4 x0, x1;
;                     if constexpr (SRC == 0) { x0 = *(const f32x4*)(xin + off); x1 = *(const f32x4*)(xin + off + 4); }
;                     else { const u32x4 w = *(const u32x4*)((SRC == 1 ? XR : XN) + off); x0 = (f32x4){bflo(w.x), bfhi(w.x), bflo(w.y), bfhi(w.y)}; x1 = (f32x4){bflo(w.z), bfhi(w.z), bflo(w.w), bfhi(w.w)}; }
;                     x0 = x0 + acc[ai][bj][m][0] * g0 * r; x1 = x1 + acc[ai][bj][m][1] * g1 * r;
;                     acc[ai][bj][m][0] = x0; acc[ai][bj][m][1] = x1;
;                     if constexpr (NEXT == 0) { *(f32x4*)(Y + off) = x0; *(f32x4*)(Y + off + 4) = x1; }
;                     else { u32x4 w; w.x = pk2(x0[0], x0[1]); w.y = pk2(x0[2], x0[3]); w.z = pk2(x1[0], x1[1]); w.w = pk2(x1[2], x1[3]); *(u32x4*)((NEXT == 1 ? XR : XN) + off) = w; }
;                 }
	v_pk_mul_f32 v[74:75], v[74:75], v[62:63]
	v_pk_mul_f32 v[72:73], v[72:73], v[60:61]
	v_pk_fma_f32 v[78:79], v[78:79], v[124:125], v[44:45] op_sel_hi:[1,0,1]
	v_pk_fma_f32 v[44:45], v[76:77], v[124:125], v[90:91] op_sel_hi:[1,0,1]
	v_pk_fma_f32 v[74:75], v[74:75], v[124:125], v[46:47] op_sel_hi:[1,0,1]
	v_pk_fma_f32 v[46:47], v[72:73], v[124:125], v[96:97] op_sel_hi:[1,0,1]
	v_cvt_pk_bf16_f32 v44, v44, v45
	v_cvt_pk_bf16_f32 v45, v78, v79
	v_cvt_pk_bf16_f32 v46, v46, v47
	v_cvt_pk_bf16_f32 v47, v74, v75
	global_store_dwordx4 v[82:83], v[44:47], off
	s_nop 1
	v_mov_b64_e32 v[44:45], v[198:199]
	v_mov_b64_e32 v[46:47], v[200:201]
	v_lshl_add_u64 v[74:75], s[2:3], 0, v[80:81]
	v_pk_mul_f32 v[66:67], v[66:67], v[54:55]
	v_pk_mul_f32 v[64:65], v[64:65], v[52:53]
	v_pk_mul_f32 v[58:59], v[58:59], v[62:63]
	v_pk_mul_f32 v[56:57], v[56:57], v[60:61]
	v_lshl_add_u64 v[72:73], v[126:127], 0, v[70:71]
	v_lshlrev_b64 v[72:73], 1, v[72:73]
	v_lshl_add_u64 v[76:77], s[4:5], 0, v[72:73]
	v_pk_mul_f32 v[50:51], v[50:51], v[54:55]
	v_pk_mul_f32 v[48:49], v[48:49], v[52:53]
	v_pk_mul_f32 v[42:43], v[42:43], v[62:63]
	v_pk_mul_f32 v[40:41], v[40:41], v[60:61]
	v_pk_mul_f32 v[38:39], v[38:39], v[54:55]
	v_pk_mul_f32 v[36:37], v[36:37], v[52:53]
	v_pk_mul_f32 v[34:35], v[34:35], v[62:63]
	v_pk_mul_f32 v[32:33], v[32:33], v[60:61]
	v_pk_mul_f32 v[30:31], v[30:31], v[54:55]
	v_pk_mul_f32 v[28:29], v[28:29], v[52:53]
	v_pk_mul_f32 v[26:27], v[26:27], v[62:63]
	v_pk_mul_f32 v[24:25], v[24:25], v[60:61]
	v_pk_mul_f32 v[22:23], v[22:23], v[54:55]
	v_pk_mul_f32 v[20:21], v[20:21], v[52:53]
	v_pk_mul_f32 v[18:19], v[18:19], v[62:63]
	v_pk_mul_f32 v[16:17], v[16:17], v[60:61]
	v_pk_mul_f32 v[14:15], v[14:15], v[54:55]
	v_pk_mul_f32 v[12:13], v[12:13], v[52:53]
	v_pk_mul_f32 v[10:11], v[10:11], v[62:63]
	v_pk_mul_f32 v[8:9], v[8:9], v[60:61]
	v_pk_mul_f32 v[6:7], v[6:7], v[54:55]
	v_pk_mul_f32 v[4:5], v[4:5], v[52:53]
	v_pk_mul_f32 v[2:3], v[2:3], v[62:63]
	v_pk_mul_f32 v[0:1], v[0:1], v[60:61]
	v_lshlrev_b32_e32 v78, 16, v44
	v_and_b32_e32 v79, 0xffff0000, v44
	v_lshlrev_b32_e32 v44, 16, v45
	v_and_b32_e32 v45, 0xffff0000, v45
	v_lshlrev_b32_e32 v80, 16, v46
	v_and_b32_e32 v81, 0xffff0000, v46
	v_lshlrev_b32_e32 v46, 16, v47
	v_and_b32_e32 v47, 0xffff0000, v47
	v_pk_fma_f32 v[66:67], v[66:67], v[116:117], v[44:45] op_sel_hi:[1,0,1]
	v_pk_fma_f32 v[44:45], v[64:65], v[116:117], v[78:79] op_sel_hi:[1,0,1]
	v_pk_fma_f32 v[58:59], v[58:59], v[116:117], v[46:47] op_sel_hi:[1,0,1]
	v_pk_fma_f32 v[46:47], v[56:57], v[116:117], v[80:81] op_sel_hi:[1,0,1]
	v_cvt_pk_bf16_f32 v44, v44, v45
	v_cvt_pk_bf16_f32 v45, v66, v67
	v_cvt_pk_bf16_f32 v46, v46, v47
	v_cvt_pk_bf16_f32 v47, v58, v59
	global_store_dwordx4 v[74:75], v[44:47], off
	s_nop 1
	v_mov_b64_e32 v[44:45], v[202:203]
	v_mov_b64_e32 v[46:47], v[204:205]
	v_lshl_add_u64 v[58:59], s[2:3], 0, v[72:73]
	v_lshl_add_u64 v[56:57], v[118:119], 0, v[70:71]
	v_lshlrev_b64 v[56:57], 1, v[56:57]
	v_lshl_add_u64 v[64:65], s[4:5], 0, v[56:57]
	v_lshlrev_b32_e32 v66, 16, v44
	v_and_b32_e32 v67, 0xffff0000, v44
	v_lshlrev_b32_e32 v44, 16, v45
	v_and_b32_e32 v45, 0xffff0000, v45
	v_lshlrev_b32_e32 v72, 16, v46
	v_and_b32_e32 v73, 0xffff0000, v46
	v_lshlrev_b32_e32 v46, 16, v47
	v_and_b32_e32 v47, 0xffff0000, v47
	v_pk_fma_f32 v[44:45], v[50:51], v[108:109], v[44:45] op_sel_hi:[1,0,1]
	v_pk_fma_f32 v[48:49], v[48:49], v[108:109], v[66:67] op_sel_hi:[1,0,1]
	v_pk_fma_f32 v[46:47], v[42:43], v[108:109], v[46:47] op_sel_hi:[1,0,1]
	v_pk_fma_f32 v[42:43], v[40:41], v[108:109], v[72:73] op_sel_hi:[1,0,1]
	v_cvt_pk_bf16_f32 v40, v48, v49
	v_cvt_pk_bf16_f32 v41, v44, v45
	v_cvt_pk_bf16_f32 v42, v42, v43
	v_cvt_pk_bf16_f32 v43, v46, v47
	global_store_dwordx4 v[58:59], v[40:43], off
	s_nop 1
	v_mov_b64_e32 v[40:41], v[206:207]
	v_mov_b64_e32 v[42:43], v[208:209]
	v_lshl_add_u64 v[46:47], s[2:3], 0, v[56:57]
	v_lshl_add_u64 v[44:45], v[110:111], 0, v[70:71]
	v_lshlrev_b64 v[44:45], 1, v[44:45]
	v_lshl_add_u64 v[48:49], s[4:5], 0, v[44:45]
	v_lshlrev_b32_e32 v50, 16, v40
	v_and_b32_e32 v51, 0xffff0000, v40
	v_lshlrev_b32_e32 v40, 16, v41
	v_and_b32_e32 v41, 0xffff0000, v41
	v_lshlrev_b32_e32 v56, 16, v42
	v_and_b32_e32 v57, 0xffff0000, v42
	v_lshlrev_b32_e32 v42, 16, v43
	v_and_b32_e32 v43, 0xffff0000, v43
; __device__ __forceinline__ float bflo(unsigned w) { return __uint_as_float(w << 16); }
; __device__ __forceinline__ float bfhi(unsigned w) { return __uint_as_float(w & 0xffff0000u); }
; __device__ __forceinline__ unsigned pk2(float lo, float hi) { f32x2 v = {lo, hi}; bf16x2_t b = __builtin_convertvector(v, bf16x2_t); return __builtin_bit_cast(unsigned, b); }
;     __device__ __forceinline__ void fused(f32x4 (&acc)[2][2][4][2], const Unit& u, int wr, int wc, int fr, int fq, LAS unsigned char* lds, int wid, int lane) const {
;     ...
;             for (int ai = 0; ai < 2; ++ai)
; #pragma unroll
;                 for (int m = 0; m < 4; ++m) {
;                     const int rl = ai * HALF + wr * 64 + m * 16 + fr; const size_t off = (size_t)(u.pm * BM + rl) * 1024 + col; const float r = S[rl];
;                     f32x4 x0, x1;
;                     if constexpr (SRC == 0) { x0 = *(const f32x4*)(xin + off); x1 = *(const f32x4*)(xin + off + 4); }
;                     else { const u32x4 w = *(const u32x4*)((SRC == 1 ? XR : XN) + off); x0 = (f32x4){bflo(w.x), bfhi(w.x), bflo(w.y), bfhi(w.y)}; x1 = (f32x4){bflo(w.z), bfhi(w.z), bflo(w.w), bfhi(w.w)}; }
;                     x0 = x0 + acc[ai][bj][m][0] * g0 * r; x1 = x1 + acc[ai][bj][m][1] * g1 * r;
;                     acc[ai][bj][m][0] = x0; acc[ai][bj][m][1] = x1;
;                     if constexpr (NEXT == 0) { *(f32x4*)(Y + off) = x0; *(f32x4*)(Y + off + 4) = x1; }
;                     else { u32x4 w; w.x = pk2(x0[0], x0[1]); w.y = pk2(x0[2], x0[3]); w.z = pk2(x1[0], x1[1]); w.w = pk2(x1[2], x1[3]); *(u32x4*)((NEXT == 1 ? XR : XN) + off) = w; }
;                 }
;         }
	v_pk_fma_f32 v[38:39], v[38:39], v[100:101], v[40:41] op_sel_hi:[1,0,1]
	v_pk_fma_f32 v[36:37], v[36:37], v[100:101], v[50:51] op_sel_hi:[1,0,1]
	v_pk_fma_f32 v[40:41], v[34:35], v[100:101], v[42:43] op_sel_hi:[1,0,1]
	v_pk_fma_f32 v[34:35], v[32:33], v[100:101], v[56:57] op_sel_hi:[1,0,1]
	v_cvt_pk_bf16_f32 v32, v36, v37
	v_cvt_pk_bf16_f32 v33, v38, v39
	v_cvt_pk_bf16_f32 v34, v34, v35
	v_cvt_pk_bf16_f32 v35, v40, v41
	global_store_dwordx4 v[46:47], v[32:35], off
	s_nop 1
	v_mov_b64_e32 v[32:33], v[210:211]
	v_mov_b64_e32 v[34:35], v[212:213]
	v_lshl_add_u64 v[38:39], s[2:3], 0, v[44:45]
	v_lshl_add_u64 v[36:37], v[102:103], 0, v[70:71]
	v_lshlrev_b64 v[36:37], 1, v[36:37]
	v_lshl_add_u64 v[40:41], s[4:5], 0, v[36:37]
	v_lshlrev_b32_e32 v42, 16, v32
	v_and_b32_e32 v43, 0xffff0000, v32
	v_lshlrev_b32_e32 v32, 16, v33
	v_and_b32_e32 v33, 0xffff0000, v33
	v_lshlrev_b32_e32 v44, 16, v34
	v_and_b32_e32 v45, 0xffff0000, v34
	v_lshlrev_b32_e32 v34, 16, v35
	v_and_b32_e32 v35, 0xffff0000, v35
	v_pk_fma_f32 v[30:31], v[30:31], v[92:93], v[32:33] op_sel_hi:[1,0,1]
	v_pk_fma_f32 v[28:29], v[28:29], v[92:93], v[42:43] op_sel_hi:[1,0,1]
	v_pk_fma_f32 v[32:33], v[26:27], v[92:93], v[34:35] op_sel_hi:[1,0,1]
	v_pk_fma_f32 v[26:27], v[24:25], v[92:93], v[44:45] op_sel_hi:[1,0,1]
	v_cvt_pk_bf16_f32 v24, v28, v29
	v_cvt_pk_bf16_f32 v25, v30, v31
	v_cvt_pk_bf16_f32 v26, v26, v27
	v_cvt_pk_bf16_f32 v27, v32, v33
	global_store_dwordx4 v[38:39], v[24:27], off
	s_nop 1
	v_mov_b64_e32 v[24:25], v[214:215]
	v_mov_b64_e32 v[26:27], v[216:217]
	v_lshl_add_u64 v[30:31], s[2:3], 0, v[36:37]
	v_lshl_add_u64 v[28:29], v[94:95], 0, v[70:71]
	v_lshlrev_b64 v[28:29], 1, v[28:29]
	v_lshl_add_u64 v[32:33], s[4:5], 0, v[28:29]
	v_lshlrev_b32_e32 v34, 16, v24
	v_and_b32_e32 v35, 0xffff0000, v24
	v_lshlrev_b32_e32 v24, 16, v25
	v_and_b32_e32 v25, 0xffff0000, v25
	v_lshlrev_b32_e32 v36, 16, v26
	v_and_b32_e32 v37, 0xffff0000, v26
	v_lshlrev_b32_e32 v26, 16, v27
	v_and_b32_e32 v27, 0xffff0000, v27
	v_pk_fma_f32 v[22:23], v[22:23], v[84:85], v[24:25] op_sel_hi:[1,0,1]
	v_pk_fma_f32 v[20:21], v[20:21], v[84:85], v[34:35] op_sel_hi:[1,0,1]
	v_pk_fma_f32 v[24:25], v[18:19], v[84:85], v[26:27] op_sel_hi:[1,0,1]
	v_pk_fma_f32 v[18:19], v[16:17], v[84:85], v[36:37] op_sel_hi:[1,0,1]
	v_cvt_pk_bf16_f32 v16, v20, v21
	v_cvt_pk_bf16_f32 v17, v22, v23
	v_cvt_pk_bf16_f32 v18, v18, v19
	v_cvt_pk_bf16_f32 v19, v24, v25
	global_store_dwordx4 v[30:31], v[16:19], off
	s_nop 1
	v_mov_b64_e32 v[16:17], v[220:221]
	v_mov_b64_e32 v[18:19], v[222:223]
	v_lshl_add_u64 v[22:23], s[2:3], 0, v[28:29]
	v_lshl_add_u64 v[20:21], v[86:87], 0, v[70:71]
	v_lshlrev_b64 v[20:21], 1, v[20:21]
	v_lshl_add_u64 v[24:25], s[4:5], 0, v[20:21]
	v_lshlrev_b32_e32 v26, 16, v16
	v_and_b32_e32 v27, 0xffff0000, v16
	v_lshlrev_b32_e32 v16, 16, v17
	v_and_b32_e32 v17, 0xffff0000, v17
	v_lshlrev_b32_e32 v28, 16, v18
	v_and_b32_e32 v29, 0xffff0000, v18
	v_lshlrev_b32_e32 v18, 16, v19
	v_and_b32_e32 v19, 0xffff0000, v19
	v_pk_fma_f32 v[14:15], v[14:15], v[68:69], v[16:17] op_sel_hi:[1,0,1]
	v_pk_fma_f32 v[12:13], v[12:13], v[68:69], v[26:27] op_sel_hi:[1,0,1]
	v_pk_fma_f32 v[16:17], v[10:11], v[68:69], v[18:19] op_sel_hi:[1,0,1]
	v_pk_fma_f32 v[10:11], v[8:9], v[68:69], v[28:29] op_sel_hi:[1,0,1]
	v_cvt_pk_bf16_f32 v8, v12, v13
	v_cvt_pk_bf16_f32 v9, v14, v15
	v_cvt_pk_bf16_f32 v10, v10, v11
	v_cvt_pk_bf16_f32 v11, v16, v17
	global_store_dwordx4 v[22:23], v[8:11], off
	s_nop 1
	v_mov_b64_e32 v[8:9], v[224:225]
	v_mov_b64_e32 v[10:11], v[226:227]
	v_lshlrev_b32_e32 v12, 16, v8
	v_and_b32_e32 v13, 0xffff0000, v8
	v_lshlrev_b32_e32 v8, 16, v9
	v_and_b32_e32 v9, 0xffff0000, v9
	v_lshlrev_b32_e32 v14, 16, v10
	v_and_b32_e32 v15, 0xffff0000, v10
	v_lshlrev_b32_e32 v10, 16, v11
	v_and_b32_e32 v11, 0xffff0000, v11
	v_pk_fma_f32 v[6:7], v[6:7], v[156:157], v[8:9] op_sel_hi:[1,0,1]
	v_pk_fma_f32 v[4:5], v[4:5], v[156:157], v[12:13] op_sel_hi:[1,0,1]
	v_pk_fma_f32 v[8:9], v[2:3], v[156:157], v[10:11] op_sel_hi:[1,0,1]
	v_pk_fma_f32 v[2:3], v[0:1], v[156:157], v[14:15] op_sel_hi:[1,0,1]
	v_cvt_pk_bf16_f32 v0, v4, v5
	v_cvt_pk_bf16_f32 v1, v6, v7
	v_cvt_pk_bf16_f32 v2, v2, v3
	v_cvt_pk_bf16_f32 v3, v8, v9
	v_lshl_add_u64 v[4:5], s[2:3], 0, v[20:21]
	global_store_dwordx4 v[4:5], v[0:3], off
	s_cmpk_gt_i32 s31, 0xff
	s_cbranch_scc1 .LBB0_1973

; __device__ __forceinline__ float bflo(unsigned w) { return __uint_as_float(w << 16); }
; __device__ __forceinline__ float bfhi(unsigned w) { return __uint_as_float(w & 0xffff0000u); }
; __device__ __forceinline__ unsigned pk2(float lo, float hi) { f32x2 v = {lo, hi}; bf16x2_t b = __builtin_convertvector(v, bf16x2_t); return __builtin_bit_cast(unsigned, b); }
;     __device__ __forceinline__ void fused(f32x4 (&acc)[2][2][4][2], const Unit& u, int wr, int wc, int fr, int fq, LAS unsigned char* lds, int wid, int lane) const {
;     ...
; #pragma unroll
;         for (int bj = 0; bj < 2; ++bj) {
;             const int col = u.pn * BM + bj * HALF + wc * 32 + 8 * fq;
;             const f32x4 g0 = *(const f32x4*)(gpost + col), g1 = *(const f32x4*)(gpost + col + 4);
; #pragma unroll
;             for (int ai = 0; ai < 2; ++ai)
; #pragma unroll
;                 for (int m = 0; m < 4; ++m) {
;                     const int rl = ai * HALF + wr * 64 + m * 16 + fr; const size_t off = (size_t)(u.pm * BM + rl) * 1024 + col; const float r = S[rl];
;                     f32x4 x0, x1;
;                     if constexpr (SRC == 0) { x0 = *(const f32x4*)(xin + off); x1 = *(const f32x4*)(xin + off + 4); }
;                     else { const u32x4 w = *(const u32x4*)((SRC == 1 ? XR : XN) + off); x0 = (f32x4){bflo(w.x), bfhi(w.x), bflo(w.y), bfhi(w.y)}; x1 = (f32x4){bflo(w.z), bfhi(w.z), bflo(w.w), bfhi(w.w)}; }
;                     x0 = x0 + acc[ai][bj][m][0] * g0 * r; x1 = x1 + acc[ai][bj][m][1] * g1 * r;
;                     acc[ai][bj][m][0] = x0; acc[ai][bj][m][1] = x1;
;                     if constexpr (NEXT == 0) { *(f32x4*)(Y + off) = x0; *(f32x4*)(Y + off + 4) = x1; }
;                     else { u32x4 w; w.x = pk2(x0[0], x0[1]); w.y = pk2(x0[2], x0[3]); w.z = pk2(x1[0], x1[1]); w.w = pk2(x1[2], x1[3]); *(u32x4*)((NEXT == 1 ? XR : XN) + off) = w; }
;                 }
.LBB0_2100:
	s_or_b64 exec, exec, s[12:13]
	v_or_b32_e32 v2, s5, v188
	v_add_u32_e32 v138, s20, v186
	v_or_b32_e32 v134, s4, v2
	v_ashrrev_i32_e32 v139, 31, v138
	v_ashrrev_i32_e32 v135, 31, v134
	v_lshlrev_b64 v[136:137], 10, v[138:139]
	v_mov_b32_e32 v0, s8
	v_mov_b32_e32 v1, s9
	v_lshl_add_u64 v[140:141], v[136:137], 0, v[134:135]
	s_waitcnt vmcnt(0) lgkmcnt(0)
	s_barrier
	v_lshl_add_u64 v[132:133], v[134:135], 2, v[0:1]
	v_lshl_add_u64 v[8:9], v[140:141], 1, s[6:7]
	global_load_dwordx4 v[0:3], v[132:133], off offset:16
	global_load_dwordx4 v[4:7], v[132:133], off
	v_lshl_add_u32 v139, v186, 2, 0
	s_mov_b32 s98, 0x8000
	s_mov_b32 s99, 0
	v_lshl_add_u64 v[252:253], v[8:9], 0, s[98:99]
	global_load_dwordx4 v[190:193], v[252:253], off
	s_mov_b32 s98, 0x10000
	s_mov_b32 s99, 0
	v_lshl_add_u64 v[252:253], v[8:9], 0, s[98:99]
	global_load_dwordx4 v[194:197], v[252:253], off
	s_mov_b32 s98, 0x18000
	s_mov_b32 s99, 0
	v_lshl_add_u64 v[252:253], v[8:9], 0, s[98:99]
	global_load_dwordx4 v[198:201], v[252:253], off
	s_mov_b32 s98, 0x40000
	s_mov_b32 s99, 0
	v_lshl_add_u64 v[252:253], v[8:9], 0, s[98:99]
	global_load_dwordx4 v[202:205], v[252:253], off
	s_mov_b32 s98, 0x48000
	s_mov_b32 s99, 0
	v_lshl_add_u64 v[252:253], v[8:9], 0, s[98:99]
	global_load_dwordx4 v[206:209], v[252:253], off
	s_mov_b32 s98, 0x50000
	s_mov_b32 s99, 0
	v_lshl_add_u64 v[252:253], v[8:9], 0, s[98:99]
	global_load_dwordx4 v[210:213], v[252:253], off
	s_mov_b32 s98, 0x58000
	s_mov_b32 s99, 0
	v_lshl_add_u64 v[252:253], v[8:9], 0, s[98:99]
	global_load_dwordx4 v[214:217], v[252:253], off
	global_load_dwordx4 v[220:223], v[8:9], off offset:256
	s_mov_b32 s98, 0x8000
	s_mov_b32 s99, 0
	v_lshl_add_u64 v[252:253], v[8:9], 0, s[98:99]
	global_load_dwordx4 v[224:227], v[252:253], off offset:256
	s_mov_b32 s98, 0x10000
	s_mov_b32 s99, 0
	v_lshl_add_u64 v[252:253], v[8:9], 0, s[98:99]
	global_load_dwordx4 v[228:231], v[252:253], off offset:256
	s_mov_b32 s98, 0x18000
	s_mov_b32 s99, 0
	v_lshl_add_u64 v[252:253], v[8:9], 0, s[98:99]
	global_load_dwordx4 v[232:235], v[252:253], off offset:256
	s_mov_b32 s98, 0x40000
	s_mov_b32 s99, 0
	v_lshl_add_u64 v[252:253], v[8:9], 0, s[98:99]
	global_load_dwordx4 v[236:239], v[252:253], off offset:256
	s_mov_b32 s98, 0x48000
	s_mov_b32 s99, 0
	v_lshl_add_u64 v[252:253], v[8:9], 0, s[98:99]
	global_load_dwordx4 v[240:243], v[252:253], off offset:256
	s_mov_b32 s98, 0x50000
	s_mov_b32 s99, 0
	v_lshl_add_u64 v[252:253], v[8:9], 0, s[98:99]
	global_load_dwordx4 v[244:247], v[252:253], off offset:256
	s_mov_b32 s98, 0x58000
	s_mov_b32 s99, 0
	v_lshl_add_u64 v[252:253], v[8:9], 0, s[98:99]
	global_load_dwordx4 v[248:251], v[252:253], off offset:256
	global_load_dwordx4 v[8:11], v[8:9], off
	ds_read_b32 v142, v139 offset:4096
	ds_read_b32 v146, v139 offset:4800
	v_add_u32_e32 v144, 16, v138
	v_ashrrev_i32_e32 v145, 31, v144
	v_lshlrev_b64 v[148:149], 10, v[144:145]
	v_lshl_add_u64 v[140:141], v[140:141], 2, s[10:11]
	v_lshl_add_u64 v[150:151], v[148:149], 0, v[134:135]
	v_lshl_add_u64 v[152:153], v[150:151], 1, s[6:7]
	v_add_u32_e32 v147, 0x1000, v139
	v_lshl_add_u64 v[150:151], v[150:151], 2, s[10:11]
	s_waitcnt vmcnt(2)
	v_pk_mul_f32 v[156:157], v[182:183], v[2:3]
	s_waitcnt vmcnt(1)
	v_pk_mul_f32 v[144:145], v[178:179], v[6:7]
	v_pk_mul_f32 v[154:155], v[180:181], v[4:5]
	s_waitcnt vmcnt(0)
	v_lshlrev_b32_e32 v160, 16, v8
	v_and_b32_e32 v161, 0xffff0000, v8
	v_lshlrev_b32_e32 v8, 16, v9
	v_and_b32_e32 v9, 0xffff0000, v9
	v_pk_mul_f32 v[158:159], v[184:185], v[0:1]
	v_lshlrev_b32_e32 v162, 16, v10
	v_and_b32_e32 v163, 0xffff0000, v10
	v_lshlrev_b32_e32 v164, 16, v11
	v_and_b32_e32 v165, 0xffff0000, v11
	s_waitcnt lgkmcnt(1)
	v_pk_fma_f32 v[10:11], v[144:145], v[142:143], v[8:9] op_sel_hi:[1,0,1]
	v_pk_fma_f32 v[8:9], v[154:155], v[142:143], v[160:161] op_sel_hi:[1,0,1]
	v_pk_fma_f32 v[144:145], v[156:157], v[142:143], v[164:165] op_sel_hi:[1,0,1]
	v_pk_fma_f32 v[142:143], v[158:159], v[142:143], v[162:163] op_sel_hi:[1,0,1]
	global_store_dwordx4 v[140:141], v[8:11], off
	global_store_dwordx4 v[140:141], v[142:145], off offset:16
	s_nop 1
	v_mov_b64_e32 v[8:9], v[190:191]
	v_mov_b64_e32 v[10:11], v[192:193]
	ds_read2_b32 v[144:145], v147 offset1:16
	v_add_u32_e32 v142, 32, v138
	v_ashrrev_i32_e32 v143, 31, v142
	v_lshlrev_b64 v[142:143], 10, v[142:143]
	v_pk_mul_f32 v[104:105], v[104:105], v[6:7]
	s_waitcnt lgkmcnt(0)
	v_mov_b32_e32 v156, v145
	v_pk_mul_f32 v[106:107], v[106:107], v[4:5]
	v_lshl_add_u64 v[152:153], v[142:143], 0, v[134:135]
	v_pk_mul_f32 v[108:109], v[108:109], v[2:3]
	v_pk_mul_f32 v[110:111], v[110:111], v[0:1]
	v_lshl_add_u64 v[154:155], v[152:153], 1, s[6:7]
	v_pk_mul_f32 v[88:89], v[88:89], v[6:7]
	v_pk_mul_f32 v[90:91], v[90:91], v[4:5]
	v_pk_mul_f32 v[92:93], v[92:93], v[2:3]
	v_pk_mul_f32 v[94:95], v[94:95], v[0:1]
	v_pk_mul_f32 v[72:73], v[72:73], v[6:7]
	v_pk_mul_f32 v[74:75], v[74:75], v[4:5]
	v_pk_mul_f32 v[76:77], v[76:77], v[2:3]
	v_pk_mul_f32 v[78:79], v[78:79], v[0:1]
	v_pk_mul_f32 v[56:57], v[56:57], v[6:7]
	v_pk_mul_f32 v[58:59], v[58:59], v[4:5]
	v_pk_mul_f32 v[60:61], v[60:61], v[2:3]
	v_pk_mul_f32 v[62:63], v[62:63], v[0:1]
	v_pk_mul_f32 v[40:41], v[40:41], v[6:7]
	v_pk_mul_f32 v[42:43], v[42:43], v[4:5]
	v_pk_mul_f32 v[44:45], v[44:45], v[2:3]
	v_pk_mul_f32 v[46:47], v[46:47], v[0:1]
	v_pk_mul_f32 v[24:25], v[24:25], v[6:7]
	v_pk_mul_f32 v[26:27], v[26:27], v[4:5]
	v_pk_mul_f32 v[28:29], v[28:29], v[2:3]
	v_pk_mul_f32 v[30:31], v[30:31], v[0:1]
	v_pk_mul_f32 v[6:7], v[124:125], v[6:7]
	v_pk_mul_f32 v[4:5], v[128:129], v[4:5]
	v_lshlrev_b32_e32 v158, 16, v8
	v_and_b32_e32 v159, 0xffff0000, v8
	v_lshlrev_b32_e32 v8, 16, v9
	v_and_b32_e32 v9, 0xffff0000, v9
	v_lshlrev_b32_e32 v160, 16, v10
	v_and_b32_e32 v161, 0xffff0000, v10
	v_lshlrev_b32_e32 v162, 16, v11
	v_and_b32_e32 v163, 0xffff0000, v11
	v_pk_fma_f32 v[10:11], v[104:105], v[156:157], v[8:9] op_sel_hi:[1,0,1]
	v_pk_fma_f32 v[8:9], v[106:107], v[156:157], v[158:159] op_sel_hi:[1,0,1]
	v_pk_fma_f32 v[106:107], v[108:109], v[156:157], v[162:163] op_sel_hi:[1,0,1]
	v_pk_fma_f32 v[104:105], v[110:111], v[156:157], v[160:161] op_sel_hi:[1,0,1]
	global_store_dwordx4 v[150:151], v[8:11], off
	global_store_dwordx4 v[150:151], v[104:107], off offset:16
	s_nop 1
	v_mov_b64_e32 v[8:9], v[194:195]
	v_mov_b64_e32 v[10:11], v[196:197]
	ds_read2_b32 v[106:107], v147 offset0:16 offset1:32
	v_add_u32_e32 v104, 48, v138
	v_ashrrev_i32_e32 v105, 31, v104
	v_lshlrev_b64 v[104:105], 10, v[104:105]
	v_lshl_add_u64 v[108:109], v[104:105], 0, v[134:135]
	s_waitcnt lgkmcnt(0)
; __device__ __forceinline__ float bflo(unsigned w) { return __uint_as_float(w << 16); }
; __device__ __forceinline__ float bfhi(unsigned w) { return __uint_as_float(w & 0xffff0000u); }
; __device__ __forceinline__ unsigned pk2(float lo, float hi) { f32x2 v = {lo, hi}; bf16x2_t b = __builtin_convertvector(v, bf16x2_t); return __builtin_bit_cast(unsigned, b); }
;     __device__ __forceinline__ void fused(f32x4 (&acc)[2][2][4][2], const Unit& u, int wr, int wc, int fr, int fq, LAS unsigned char* lds, int wid, int lane) const {
;     ...
;         for (int bj = 0; bj < 2; ++bj) {
;             const int col = u.pn * BM + bj * HALF + wc * 32 + 8 * fq;
;             const f32x4 g0 = *(const f32x4*)(gpost + col), g1 = *(const f32x4*)(gpost + col + 4);
; #pragma unroll
;             for (int ai = 0; ai < 2; ++ai)
; #pragma unroll
;                 for (int m = 0; m < 4; ++m) {
;                     const int rl = ai * HALF + wr * 64 + m * 16 + fr; const size_t off = (size_t)(u.pm * BM + rl) * 1024 + col; const float r = S[rl];
;                     f32x4 x0, x1;
;                     if constexpr (SRC == 0) { x0 = *(const f32x4*)(xin + off); x1 = *(const f32x4*)(xin + off + 4); }
;                     else { const u32x4 w = *(const u32x4*)((SRC == 1 ? XR : XN) + off); x0 = (f32x4){bflo(w.x), bfhi(w.x), bflo(w.y), bfhi(w.y)}; x1 = (f32x4){bflo(w.z), bfhi(w.z), bflo(w.w), bfhi(w.w)}; }
;                     x0 = x0 + acc[ai][bj][m][0] * g0 * r; x1 = x1 + acc[ai][bj][m][1] * g1 * r;
;                     acc[ai][bj][m][0] = x0; acc[ai][bj][m][1] = x1;
;                     if constexpr (NEXT == 0) { *(f32x4*)(Y + off) = x0; *(f32x4*)(Y + off + 4) = x1; }
;                     else { u32x4 w; w.x = pk2(x0[0], x0[1]); w.y = pk2(x0[2], x0[3]); w.z = pk2(x1[0], x1[1]); w.w = pk2(x1[2], x1[3]); *(u32x4*)((NEXT == 1 ? XR : XN) + off) = w; }
	v_mov_b32_e32 v154, v107
	v_lshl_add_u64 v[110:111], v[152:153], 2, s[10:11]
	v_lshl_add_u64 v[152:153], v[108:109], 1, s[6:7]
	v_lshlrev_b32_e32 v156, 16, v8
	v_and_b32_e32 v157, 0xffff0000, v8
	v_lshlrev_b32_e32 v8, 16, v9
	v_and_b32_e32 v9, 0xffff0000, v9
	v_lshlrev_b32_e32 v158, 16, v10
	v_and_b32_e32 v159, 0xffff0000, v10
	v_lshlrev_b32_e32 v160, 16, v11
	v_and_b32_e32 v161, 0xffff0000, v11
	v_pk_fma_f32 v[10:11], v[88:89], v[154:155], v[8:9] op_sel_hi:[1,0,1]
	v_pk_fma_f32 v[8:9], v[90:91], v[154:155], v[156:157] op_sel_hi:[1,0,1]
	v_pk_fma_f32 v[90:91], v[92:93], v[154:155], v[160:161] op_sel_hi:[1,0,1]
	v_pk_fma_f32 v[88:89], v[94:95], v[154:155], v[158:159] op_sel_hi:[1,0,1]
	global_store_dwordx4 v[110:111], v[8:11], off
	global_store_dwordx4 v[110:111], v[88:91], off offset:16
	s_nop 1
	v_mov_b64_e32 v[8:9], v[198:199]
	v_mov_b64_e32 v[10:11], v[200:201]
	ds_read2_b32 v[90:91], v147 offset0:32 offset1:48
	v_add_u32_e32 v88, 0x80, v138
	v_ashrrev_i32_e32 v89, 31, v88
	v_lshlrev_b64 v[88:89], 10, v[88:89]
	v_lshl_add_u64 v[92:93], v[88:89], 0, v[134:135]
	s_waitcnt lgkmcnt(0)
	v_mov_b32_e32 v152, v91
	v_lshl_add_u64 v[94:95], v[108:109], 2, s[10:11]
	v_lshl_add_u64 v[108:109], v[92:93], 1, s[6:7]
	v_lshlrev_b32_e32 v154, 16, v8
	v_and_b32_e32 v155, 0xffff0000, v8
	v_lshlrev_b32_e32 v8, 16, v9
	v_and_b32_e32 v9, 0xffff0000, v9
	v_lshlrev_b32_e32 v156, 16, v10
	v_and_b32_e32 v157, 0xffff0000, v10
	v_lshlrev_b32_e32 v158, 16, v11
	v_and_b32_e32 v159, 0xffff0000, v11
	v_pk_fma_f32 v[10:11], v[72:73], v[152:153], v[8:9] op_sel_hi:[1,0,1]
	v_pk_fma_f32 v[8:9], v[74:75], v[152:153], v[154:155] op_sel_hi:[1,0,1]
	v_pk_fma_f32 v[74:75], v[76:77], v[152:153], v[158:159] op_sel_hi:[1,0,1]
	v_pk_fma_f32 v[72:73], v[78:79], v[152:153], v[156:157] op_sel_hi:[1,0,1]
	global_store_dwordx4 v[94:95], v[8:11], off
	global_store_dwordx4 v[94:95], v[72:75], off offset:16
	s_nop 1
	v_mov_b64_e32 v[8:9], v[202:203]
	v_mov_b64_e32 v[10:11], v[204:205]
	ds_read2_b32 v[74:75], v147 offset0:48 offset1:128
	v_add_u32_e32 v72, 0x90, v138
	v_ashrrev_i32_e32 v73, 31, v72
	v_lshlrev_b64 v[72:73], 10, v[72:73]
	v_lshl_add_u64 v[76:77], v[72:73], 0, v[134:135]
	s_waitcnt lgkmcnt(0)
	v_mov_b32_e32 v108, v75
	v_lshl_add_u64 v[78:79], v[92:93], 2, s[10:11]
	v_lshl_add_u64 v[92:93], v[76:77], 1, s[6:7]
	v_lshlrev_b32_e32 v152, 16, v8
	v_and_b32_e32 v153, 0xffff0000, v8
	v_lshlrev_b32_e32 v8, 16, v9
	v_and_b32_e32 v9, 0xffff0000, v9
	v_lshlrev_b32_e32 v154, 16, v10
	v_and_b32_e32 v155, 0xffff0000, v10
	v_lshlrev_b32_e32 v156, 16, v11
	v_and_b32_e32 v157, 0xffff0000, v11
	v_pk_fma_f32 v[10:11], v[56:57], v[108:109], v[8:9] op_sel_hi:[1,0,1]
	v_pk_fma_f32 v[8:9], v[58:59], v[108:109], v[152:153] op_sel_hi:[1,0,1]
	v_pk_fma_f32 v[58:59], v[60:61], v[108:109], v[156:157] op_sel_hi:[1,0,1]
	v_pk_fma_f32 v[56:57], v[62:63], v[108:109], v[154:155] op_sel_hi:[1,0,1]
	global_store_dwordx4 v[78:79], v[8:11], off
	global_store_dwordx4 v[78:79], v[56:59], off offset:16
	s_nop 1
	v_mov_b64_e32 v[8:9], v[206:207]
	v_mov_b64_e32 v[10:11], v[208:209]
	ds_read2_b32 v[58:59], v147 offset0:128 offset1:144
	v_add_u32_e32 v56, 0xa0, v138
	v_ashrrev_i32_e32 v57, 31, v56
	v_lshlrev_b64 v[56:57], 10, v[56:57]
	v_lshl_add_u64 v[60:61], v[56:57], 0, v[134:135]
	s_waitcnt lgkmcnt(0)
	v_mov_b32_e32 v92, v59
	v_lshl_add_u64 v[62:63], v[76:77], 2, s[10:11]
	v_lshl_add_u64 v[76:77], v[60:61], 1, s[6:7]
	v_lshlrev_b32_e32 v108, 16, v8
	v_and_b32_e32 v109, 0xffff0000, v8
	v_lshlrev_b32_e32 v8, 16, v9
	v_and_b32_e32 v9, 0xffff0000, v9
	v_lshlrev_b32_e32 v152, 16, v10
	v_and_b32_e32 v153, 0xffff0000, v10
	v_lshlrev_b32_e32 v154, 16, v11
	v_and_b32_e32 v155, 0xffff0000, v11
	v_pk_fma_f32 v[10:11], v[40:41], v[92:93], v[8:9] op_sel_hi:[1,0,1]
	v_pk_fma_f32 v[8:9], v[42:43], v[92:93], v[108:109] op_sel_hi:[1,0,1]
	v_pk_fma_f32 v[42:43], v[44:45], v[92:93], v[154:155] op_sel_hi:[1,0,1]
	v_pk_fma_f32 v[40:41], v[46:47], v[92:93], v[152:153] op_sel_hi:[1,0,1]
	global_store_dwordx4 v[62:63], v[8:11], off
	global_store_dwordx4 v[62:63], v[40:43], off offset:16
	s_nop 1
	v_mov_b64_e32 v[8:9], v[210:211]
	v_mov_b64_e32 v[10:11], v[212:213]
	ds_read2_b32 v[42:43], v147 offset0:144 offset1:160
	v_add_u32_e32 v40, 0xb0, v138
	v_ashrrev_i32_e32 v41, 31, v40
	v_lshlrev_b64 v[40:41], 10, v[40:41]
	v_lshl_add_u64 v[44:45], v[40:41], 0, v[134:135]
	s_waitcnt lgkmcnt(0)
	v_mov_b32_e32 v76, v43
	v_lshl_add_u64 v[46:47], v[60:61], 2, s[10:11]
	v_lshl_add_u64 v[60:61], v[44:45], 1, s[6:7]
	v_lshl_add_u64 v[44:45], v[44:45], 2, s[10:11]
	v_lshlrev_b32_e32 v92, 16, v8
	v_and_b32_e32 v93, 0xffff0000, v8
	v_lshlrev_b32_e32 v8, 16, v9
	v_and_b32_e32 v9, 0xffff0000, v9
	v_lshlrev_b32_e32 v108, 16, v10
	v_and_b32_e32 v109, 0xffff0000, v10
	v_lshlrev_b32_e32 v138, 16, v11
	v_and_b32_e32 v139, 0xffff0000, v11
	v_pk_fma_f32 v[10:11], v[24:25], v[76:77], v[8:9] op_sel_hi:[1,0,1]
	v_pk_fma_f32 v[8:9], v[26:27], v[76:77], v[92:93] op_sel_hi:[1,0,1]
	v_pk_fma_f32 v[26:27], v[28:29], v[76:77], v[138:139] op_sel_hi:[1,0,1]
	v_pk_fma_f32 v[24:25], v[30:31], v[76:77], v[108:109] op_sel_hi:[1,0,1]
	global_store_dwordx4 v[46:47], v[8:11], off
	global_store_dwordx4 v[46:47], v[24:27], off offset:16
	s_nop 1
	v_mov_b64_e32 v[8:9], v[214:215]
	v_mov_b64_e32 v[10:11], v[216:217]
	ds_read2_b32 v[28:29], v147 offset0:160 offset1:176
	v_or_b32_e32 v30, 0x80, v134
	v_ashrrev_i32_e32 v31, 31, v30
	v_pk_mul_f32 v[60:61], v[126:127], v[2:3]
	v_pk_mul_f32 v[76:77], v[130:131], v[0:1]
	s_waitcnt lgkmcnt(0)
; __device__ __forceinline__ float bflo(unsigned w) { return __uint_as_float(w << 16); }
; __device__ __forceinline__ float bfhi(unsigned w) { return __uint_as_float(w & 0xffff0000u); }
; __device__ __forceinline__ unsigned pk2(float lo, float hi) { f32x2 v = {lo, hi}; bf16x2_t b = __builtin_convertvector(v, bf16x2_t); return __builtin_bit_cast(unsigned, b); }
;     __device__ __forceinline__ void fused(f32x4 (&acc)[2][2][4][2], const Unit& u, int wr, int wc, int fr, int fq, LAS unsigned char* lds, int wid, int lane) const {
;     ...
;         for (int bj = 0; bj < 2; ++bj) {
;             const int col = u.pn * BM + bj * HALF + wc * 32 + 8 * fq;
;             const f32x4 g0 = *(const f32x4*)(gpost + col), g1 = *(const f32x4*)(gpost + col + 4);
; #pragma unroll
;             for (int ai = 0; ai < 2; ++ai)
; #pragma unroll
;                 for (int m = 0; m < 4; ++m) {
;                     const int rl = ai * HALF + wr * 64 + m * 16 + fr; const size_t off = (size_t)(u.pm * BM + rl) * 1024 + col; const float r = S[rl];
;                     f32x4 x0, x1;
;                     if constexpr (SRC == 0) { x0 = *(const f32x4*)(xin + off); x1 = *(const f32x4*)(xin + off + 4); }
;                     else { const u32x4 w = *(const u32x4*)((SRC == 1 ? XR : XN) + off); x0 = (f32x4){bflo(w.x), bfhi(w.x), bflo(w.y), bfhi(w.y)}; x1 = (f32x4){bflo(w.z), bfhi(w.z), bflo(w.w), bfhi(w.w)}; }
;                     x0 = x0 + acc[ai][bj][m][0] * g0 * r; x1 = x1 + acc[ai][bj][m][1] * g1 * r;
;                     acc[ai][bj][m][0] = x0; acc[ai][bj][m][1] = x1;
;                     if constexpr (NEXT == 0) { *(f32x4*)(Y + off) = x0; *(f32x4*)(Y + off + 4) = x1; }
;                     else { u32x4 w; w.x = pk2(x0[0], x0[1]); w.y = pk2(x0[2], x0[3]); w.z = pk2(x1[0], x1[1]); w.w = pk2(x1[2], x1[3]); *(u32x4*)((NEXT == 1 ? XR : XN) + off) = w; }
;                 }
	v_mov_b32_e32 v26, v29
	v_lshl_add_u64 v[24:25], v[136:137], 0, v[30:31]
	v_lshl_add_u64 v[24:25], v[24:25], 1, s[6:7]
	v_lshlrev_b32_e32 v0, 16, v8
	v_and_b32_e32 v1, 0xffff0000, v8
	v_lshlrev_b32_e32 v2, 16, v9
	v_and_b32_e32 v3, 0xffff0000, v9
	v_lshlrev_b32_e32 v8, 16, v10
	v_and_b32_e32 v9, 0xffff0000, v10
	v_lshlrev_b32_e32 v10, 16, v11
	v_and_b32_e32 v11, 0xffff0000, v11
	v_pk_fma_f32 v[2:3], v[6:7], v[26:27], v[2:3] op_sel_hi:[1,0,1]
	v_pk_fma_f32 v[0:1], v[4:5], v[26:27], v[0:1] op_sel_hi:[1,0,1]
	v_pk_fma_f32 v[6:7], v[60:61], v[26:27], v[10:11] op_sel_hi:[1,0,1]
	v_pk_fma_f32 v[4:5], v[76:77], v[26:27], v[8:9] op_sel_hi:[1,0,1]
	global_store_dwordx4 v[44:45], v[0:3], off
	global_store_dwordx4 v[44:45], v[4:7], off offset:16
	s_nop 1
	v_mov_b64_e32 v[0:1], v[220:221]
	v_mov_b64_e32 v[2:3], v[222:223]
	s_nop 0
	global_load_dwordx4 v[4:7], v[132:133], off offset:512
	global_load_dwordx4 v[8:11], v[132:133], off offset:528
	v_lshl_add_u64 v[24:25], v[148:149], 0, v[30:31]
	v_lshl_add_u64 v[60:61], v[24:25], 1, s[6:7]
	v_lshlrev_b32_e32 v24, 16, v0
	v_and_b32_e32 v25, 0xffff0000, v0
	v_lshlrev_b32_e32 v0, 16, v1
	v_and_b32_e32 v1, 0xffff0000, v1
	v_lshlrev_b32_e32 v76, 16, v2
	v_and_b32_e32 v77, 0xffff0000, v2
	v_lshlrev_b32_e32 v26, 16, v3
	v_and_b32_e32 v27, 0xffff0000, v3
	s_waitcnt vmcnt(1)
	v_pk_mul_f32 v[2:3], v[112:113], v[6:7]
	v_pk_mul_f32 v[92:93], v[114:115], v[4:5]
	s_waitcnt vmcnt(0)
	v_pk_mul_f32 v[108:109], v[116:117], v[10:11]
	v_pk_mul_f32 v[112:113], v[118:119], v[8:9]
	v_pk_fma_f32 v[2:3], v[2:3], v[144:145], v[0:1] op_sel_hi:[1,0,1]
	v_pk_fma_f32 v[0:1], v[92:93], v[144:145], v[24:25] op_sel_hi:[1,0,1]
	v_pk_fma_f32 v[26:27], v[108:109], v[144:145], v[26:27] op_sel_hi:[1,0,1]
	v_pk_fma_f32 v[24:25], v[112:113], v[144:145], v[76:77] op_sel_hi:[1,0,1]
	global_store_dwordx4 v[140:141], v[0:3], off offset:512
	global_store_dwordx4 v[140:141], v[24:27], off offset:528
	s_nop 1
	v_mov_b64_e32 v[0:1], v[224:225]
	v_mov_b64_e32 v[2:3], v[226:227]
	v_pk_mul_f32 v[76:77], v[100:101], v[10:11]
	v_lshl_add_u64 v[24:25], v[142:143], 0, v[30:31]
	v_lshl_add_u64 v[60:61], v[24:25], 1, s[6:7]
	v_pk_mul_f32 v[24:25], v[96:97], v[6:7]
	v_pk_mul_f32 v[26:27], v[98:99], v[4:5]
	v_pk_mul_f32 v[92:93], v[102:103], v[8:9]
	v_pk_mul_f32 v[16:17], v[16:17], v[6:7]
	v_pk_mul_f32 v[18:19], v[18:19], v[4:5]
	v_pk_mul_f32 v[20:21], v[20:21], v[10:11]
	v_pk_mul_f32 v[22:23], v[22:23], v[8:9]
	v_lshlrev_b32_e32 v96, 16, v0
	v_and_b32_e32 v97, 0xffff0000, v0
	v_lshlrev_b32_e32 v0, 16, v1
	v_and_b32_e32 v1, 0xffff0000, v1
	v_lshlrev_b32_e32 v98, 16, v2
	v_and_b32_e32 v99, 0xffff0000, v2
	v_lshlrev_b32_e32 v100, 16, v3
	v_and_b32_e32 v101, 0xffff0000, v3
	v_pk_fma_f32 v[2:3], v[24:25], v[106:107], v[0:1] op_sel_hi:[1,0,1]
	v_pk_fma_f32 v[0:1], v[26:27], v[106:107], v[96:97] op_sel_hi:[1,0,1]
	v_pk_fma_f32 v[26:27], v[76:77], v[106:107], v[100:101] op_sel_hi:[1,0,1]
	v_pk_fma_f32 v[24:25], v[92:93], v[106:107], v[98:99] op_sel_hi:[1,0,1]
	global_store_dwordx4 v[150:151], v[0:3], off offset:512
	global_store_dwordx4 v[150:151], v[24:27], off offset:528
	s_nop 1
	v_mov_b64_e32 v[0:1], v[228:229]
	v_mov_b64_e32 v[2:3], v[230:231]
	v_pk_mul_f32 v[76:77], v[84:85], v[10:11]
	v_lshl_add_u64 v[24:25], v[104:105], 0, v[30:31]
	v_lshl_add_u64 v[60:61], v[24:25], 1, s[6:7]
	v_pk_mul_f32 v[24:25], v[80:81], v[6:7]
	v_pk_mul_f32 v[26:27], v[82:83], v[4:5]
	v_pk_mul_f32 v[80:81], v[86:87], v[8:9]
	v_lshlrev_b32_e32 v82, 16, v0
	v_and_b32_e32 v83, 0xffff0000, v0
	v_lshlrev_b32_e32 v0, 16, v1
	v_and_b32_e32 v1, 0xffff0000, v1
	v_lshlrev_b32_e32 v84, 16, v2
	v_and_b32_e32 v85, 0xffff0000, v2
	v_lshlrev_b32_e32 v86, 16, v3
	v_and_b32_e32 v87, 0xffff0000, v3
	v_pk_fma_f32 v[2:3], v[24:25], v[90:91], v[0:1] op_sel_hi:[1,0,1]
	v_pk_fma_f32 v[0:1], v[26:27], v[90:91], v[82:83] op_sel_hi:[1,0,1]
	v_pk_fma_f32 v[26:27], v[76:77], v[90:91], v[86:87] op_sel_hi:[1,0,1]
	v_pk_fma_f32 v[24:25], v[80:81], v[90:91], v[84:85] op_sel_hi:[1,0,1]
	global_store_dwordx4 v[110:111], v[0:3], off offset:512
	global_store_dwordx4 v[110:111], v[24:27], off offset:528
	s_nop 1
	v_mov_b64_e32 v[0:1], v[232:233]
	v_mov_b64_e32 v[2:3], v[234:235]
	v_lshlrev_b32_e32 v76, 16, v3
	v_lshl_add_u64 v[24:25], v[88:89], 0, v[30:31]
	v_lshl_add_u64 v[60:61], v[24:25], 1, s[6:7]
	v_pk_mul_f32 v[24:25], v[64:65], v[6:7]
	v_pk_mul_f32 v[26:27], v[66:67], v[4:5]
	v_pk_mul_f32 v[64:65], v[68:69], v[10:11]
; __device__ __forceinline__ float bflo(unsigned w) { return __uint_as_float(w << 16); }
; __device__ __forceinline__ float bfhi(unsigned w) { return __uint_as_float(w & 0xffff0000u); }
; __device__ __forceinline__ unsigned pk2(float lo, float hi) { f32x2 v = {lo, hi}; bf16x2_t b = __builtin_convertvector(v, bf16x2_t); return __builtin_bit_cast(unsigned, b); }
;     __device__ __forceinline__ void fused(f32x4 (&acc)[2][2][4][2], const Unit& u, int wr, int wc, int fr, int fq, LAS unsigned char* lds, int wid, int lane) const {
;     ...
;         for (int bj = 0; bj < 2; ++bj) {
;             const int col = u.pn * BM + bj * HALF + wc * 32 + 8 * fq;
;             const f32x4 g0 = *(const f32x4*)(gpost + col), g1 = *(const f32x4*)(gpost + col + 4);
; #pragma unroll
;             for (int ai = 0; ai < 2; ++ai)
; #pragma unroll
;                 for (int m = 0; m < 4; ++m) {
;                     const int rl = ai * HALF + wr * 64 + m * 16 + fr; const size_t off = (size_t)(u.pm * BM + rl) * 1024 + col; const float r = S[rl];
;                     f32x4 x0, x1;
;                     if constexpr (SRC == 0) { x0 = *(const f32x4*)(xin + off); x1 = *(const f32x4*)(xin + off + 4); }
;                     else { const u32x4 w = *(const u32x4*)((SRC == 1 ? XR : XN) + off); x0 = (f32x4){bflo(w.x), bfhi(w.x), bflo(w.y), bfhi(w.y)}; x1 = (f32x4){bflo(w.z), bfhi(w.z), bflo(w.w), bfhi(w.w)}; }
;                     x0 = x0 + acc[ai][bj][m][0] * g0 * r; x1 = x1 + acc[ai][bj][m][1] * g1 * r;
;                     acc[ai][bj][m][0] = x0; acc[ai][bj][m][1] = x1;
;                     if constexpr (NEXT == 0) { *(f32x4*)(Y + off) = x0; *(f32x4*)(Y + off + 4) = x1; }
;                     else { u32x4 w; w.x = pk2(x0[0], x0[1]); w.y = pk2(x0[2], x0[3]); w.z = pk2(x1[0], x1[1]); w.w = pk2(x1[2], x1[3]); *(u32x4*)((NEXT == 1 ? XR : XN) + off) = w; }
;                 }
	v_lshlrev_b32_e32 v68, 16, v0
	v_and_b32_e32 v69, 0xffff0000, v0
	v_lshlrev_b32_e32 v0, 16, v1
	v_and_b32_e32 v1, 0xffff0000, v1
	v_pk_mul_f32 v[66:67], v[70:71], v[8:9]
	v_lshlrev_b32_e32 v70, 16, v2
	v_and_b32_e32 v71, 0xffff0000, v2
	v_and_b32_e32 v77, 0xffff0000, v3
	v_pk_fma_f32 v[2:3], v[24:25], v[74:75], v[0:1] op_sel_hi:[1,0,1]
	v_pk_fma_f32 v[0:1], v[26:27], v[74:75], v[68:69] op_sel_hi:[1,0,1]
	v_pk_fma_f32 v[26:27], v[64:65], v[74:75], v[76:77] op_sel_hi:[1,0,1]
	v_pk_fma_f32 v[24:25], v[66:67], v[74:75], v[70:71] op_sel_hi:[1,0,1]
	global_store_dwordx4 v[94:95], v[0:3], off offset:512
	global_store_dwordx4 v[94:95], v[24:27], off offset:528
	s_nop 1
	v_mov_b64_e32 v[0:1], v[236:237]
	v_mov_b64_e32 v[2:3], v[238:239]
	v_lshlrev_b32_e32 v64, 16, v3
	v_lshl_add_u64 v[24:25], v[72:73], 0, v[30:31]
	v_lshl_add_u64 v[60:61], v[24:25], 1, s[6:7]
	v_pk_mul_f32 v[24:25], v[48:49], v[6:7]
	v_pk_mul_f32 v[26:27], v[50:51], v[4:5]
	v_pk_mul_f32 v[48:49], v[52:53], v[10:11]
	v_lshlrev_b32_e32 v52, 16, v0
	v_and_b32_e32 v53, 0xffff0000, v0
	v_lshlrev_b32_e32 v0, 16, v1
	v_and_b32_e32 v1, 0xffff0000, v1
	v_pk_mul_f32 v[50:51], v[54:55], v[8:9]
	v_lshlrev_b32_e32 v54, 16, v2
	v_and_b32_e32 v55, 0xffff0000, v2
	v_and_b32_e32 v65, 0xffff0000, v3
	v_pk_fma_f32 v[2:3], v[24:25], v[58:59], v[0:1] op_sel_hi:[1,0,1]
	v_pk_fma_f32 v[0:1], v[26:27], v[58:59], v[52:53] op_sel_hi:[1,0,1]
	v_pk_fma_f32 v[26:27], v[48:49], v[58:59], v[64:65] op_sel_hi:[1,0,1]
	v_pk_fma_f32 v[24:25], v[50:51], v[58:59], v[54:55] op_sel_hi:[1,0,1]
	global_store_dwordx4 v[78:79], v[0:3], off offset:512
	global_store_dwordx4 v[78:79], v[24:27], off offset:528
	s_nop 1
	v_mov_b64_e32 v[0:1], v[240:241]
	v_mov_b64_e32 v[2:3], v[242:243]
	v_lshlrev_b32_e32 v50, 16, v3
	v_lshl_add_u64 v[24:25], v[56:57], 0, v[30:31]
	v_lshl_add_u64 v[48:49], v[24:25], 1, s[6:7]
	v_pk_mul_f32 v[24:25], v[32:33], v[6:7]
	v_pk_mul_f32 v[26:27], v[34:35], v[4:5]
	v_pk_mul_f32 v[32:33], v[36:37], v[10:11]
	v_lshlrev_b32_e32 v36, 16, v0
	v_and_b32_e32 v37, 0xffff0000, v0
	v_lshlrev_b32_e32 v0, 16, v1
	v_and_b32_e32 v1, 0xffff0000, v1
	v_pk_mul_f32 v[34:35], v[38:39], v[8:9]
	v_lshlrev_b32_e32 v38, 16, v2
	v_and_b32_e32 v39, 0xffff0000, v2
	v_and_b32_e32 v51, 0xffff0000, v3
	v_pk_fma_f32 v[2:3], v[24:25], v[42:43], v[0:1] op_sel_hi:[1,0,1]
	v_pk_fma_f32 v[0:1], v[26:27], v[42:43], v[36:37] op_sel_hi:[1,0,1]
	v_pk_fma_f32 v[26:27], v[32:33], v[42:43], v[50:51] op_sel_hi:[1,0,1]
	v_pk_fma_f32 v[24:25], v[34:35], v[42:43], v[38:39] op_sel_hi:[1,0,1]
	global_store_dwordx4 v[62:63], v[0:3], off offset:512
	global_store_dwordx4 v[62:63], v[24:27], off offset:528
	s_nop 1
	v_mov_b64_e32 v[0:1], v[244:245]
	v_mov_b64_e32 v[2:3], v[246:247]
	v_pk_mul_f32 v[6:7], v[12:13], v[6:7]
	v_lshl_add_u64 v[24:25], v[40:41], 0, v[30:31]
	v_lshl_add_u64 v[24:25], v[24:25], 1, s[6:7]
	v_pk_mul_f32 v[4:5], v[120:121], v[4:5]
	v_pk_mul_f32 v[10:11], v[14:15], v[10:11]
	v_pk_mul_f32 v[8:9], v[122:123], v[8:9]
	v_lshlrev_b32_e32 v26, 16, v0
	v_and_b32_e32 v27, 0xffff0000, v0
	v_lshlrev_b32_e32 v0, 16, v1
	v_and_b32_e32 v1, 0xffff0000, v1
	v_lshlrev_b32_e32 v30, 16, v2
	v_and_b32_e32 v31, 0xffff0000, v2
	v_lshlrev_b32_e32 v32, 16, v3
	v_and_b32_e32 v33, 0xffff0000, v3
	v_pk_fma_f32 v[2:3], v[16:17], v[28:29], v[0:1] op_sel_hi:[1,0,1]
	v_pk_fma_f32 v[0:1], v[18:19], v[28:29], v[26:27] op_sel_hi:[1,0,1]
	v_pk_fma_f32 v[18:19], v[20:21], v[28:29], v[32:33] op_sel_hi:[1,0,1]
	v_pk_fma_f32 v[16:17], v[22:23], v[28:29], v[30:31] op_sel_hi:[1,0,1]
	global_store_dwordx4 v[46:47], v[0:3], off offset:512
	global_store_dwordx4 v[46:47], v[16:19], off offset:528
	s_nop 1
	v_mov_b64_e32 v[0:1], v[248:249]
	v_mov_b64_e32 v[2:3], v[250:251]
	v_lshlrev_b32_e32 v12, 16, v0
	v_and_b32_e32 v13, 0xffff0000, v0
	v_lshlrev_b32_e32 v0, 16, v1
	v_and_b32_e32 v1, 0xffff0000, v1
	v_lshlrev_b32_e32 v14, 16, v2
	v_and_b32_e32 v15, 0xffff0000, v2
	v_lshlrev_b32_e32 v16, 16, v3
	v_and_b32_e32 v17, 0xffff0000, v3
	v_pk_fma_f32 v[2:3], v[6:7], v[146:147], v[0:1] op_sel_hi:[1,0,1]
	v_pk_fma_f32 v[0:1], v[4:5], v[146:147], v[12:13] op_sel_hi:[1,0,1]
	v_pk_fma_f32 v[6:7], v[10:11], v[146:147], v[16:17] op_sel_hi:[1,0,1]
	v_pk_fma_f32 v[4:5], v[8:9], v[146:147], v[14:15] op_sel_hi:[1,0,1]
	global_store_dwordx4 v[44:45], v[0:3], off offset:512
	global_store_dwordx4 v[44:45], v[4:7], off offset:528
	s_cmpk_gt_i32 s42, 0xff
	s_cbranch_scc1 .LBB0_2115
